# P5 gMLP transposed v image: the four 32-channel blocks offset by 16 B so the four lanes of a token write different LDS banks
# speedup vs baseline: 1.0068x; 1.0005x over previous
; #define LAS __attribute__((address_space(3)))
; template <bool PASS2>
; __device__ __forceinline__ void s5_tile(const Ctx& C, int T, int sb_lo, int sb_hi, LAS unsigned char* lds, int wave, int lane) {
;     ...
;     LAS bf16* XU = (LAS bf16*)(lds + wave * S5W_BYTES);
;     LAS bf16* BH = XU + 32 * XU_STRIDE;
;     const int tl = lane & 31, hh = lane >> 5, fr = lane & 15, kq = lane >> 4, xrow = lane >> 3, xpart = lane & 7;
; __device__ __forceinline__ void gmlp_tile(const Ctx& C, int T, LAS unsigned char* lds, int wave, int lane, int tid) {
;     const int mode = (T == NTILE - 1) ? 1 : 0;
;     const int r0 = T * 128;
;     LAS bf16* VT = (LAS bf16*)lds;
;     LAS float* SSQ = (LAS float*)(lds + 128 * VT_STRIDE * 2);
;     const int tb = wave & 3, dh = wave >> 2, tl = lane & 31, hh = lane >> 5;
;     const int t = 32 * tb + tl;
;     unsigned outp[4][2][8]; float ssq = 0.f;
;     const bf16* zt = C.Z() + (size_t)(r0 + t) * DIN;
;     const int row = tid >> 2, q = tid & 3;
;     const bf16* vsrc = C.Z() + (size_t)(r0 + row) * DIN + 512 + q * 32;
.LBB0_593:
	s_or_b64 exec, exec, s[8:9]
	s_cmpk_lt_i32 s33, 0x100
	v_mov_b32_e32 v81, v182
	s_cselect_b64 s[10:11], -1, 0
	s_cmpk_gt_i32 s33, 0xff
	s_waitcnt lgkmcnt(0)
	s_barrier
	s_cbranch_scc1 .LBB0_604
	v_and_b32_e32 v1, 7, v81
	v_lshlrev_b32_e32 v0, 3, v1
	v_bfe_u32 v2, v81, 5, 1
	v_lshlrev_b32_e32 v91, 4, v1
	v_lshlrev_b32_e32 v1, 5, v81
	v_and_b32_e32 v80, 63, v81
	v_lshlrev_b32_e32 v84, 3, v2
	v_ashrrev_i32_e32 v173, 2, v81
	v_and_b32_e32 v86, 0x60, v1
	v_and_b32_e32 v85, 31, v81
	v_bfe_u32 v87, v81, 3, 3
	v_mov_b32_e32 v83, 0
	v_lshlrev_b32_e32 v169, 4, v2
	v_lshlrev_b32_e32 v88, 2, v2
	v_lshlrev_b32_e32 v1, 1, v173
	v_mul_u32_u24_e32 v2, 0x110, v86
	s_lshl_b32 s12, s33, 7
	v_lshlrev_b32_e32 v92, 4, v80
	v_lshlrev_b32_e32 v96, 1, v84
	v_or_b32_e32 v89, 0x800, v80
	v_mul_u32_u24_e32 v168, 0x90, v85
	s_movk_i32 s30, 0x110
	v_mul_u32_u24_e32 v170, 0x110, v85
	v_lshlrev_b32_e32 v171, 2, v80
	v_mul_u32_u24_e32 v172, 0x90, v87
	v_add_u32_e32 v90, 0, v169
	v_add3_u32 v174, 0, v1, v2
	v_lshrrev_b32_e32 v2, 1, v86
	v_add_u32_e32 v174, v174, v2
	v_cmp_gt_u32_e64 s[8:9], 32, v80
	v_or_b32_e32 v175, s12, v87
	s_lshl_b32 s31, s94, 7
	v_mov_b32_e32 v93, v83
	v_add_u32_e32 v176, 0, v92
	v_lshlrev_b32_e32 v94, 1, v0
	v_mov_b32_e32 v95, v83
	s_mov_b64 s[14:15], 0xb200800
	s_movk_i32 s34, 0xc00
	v_mov_b32_e32 v98, v96
	v_mov_b32_e32 v99, v83
	s_mov_b64 s[16:17], 0x2a00000
	s_mov_b32 s35, 0x2b00000
	s_mov_b64 s[18:19], 0xb200400
	s_mov_b32 s36, 0xb200000
	v_lshlrev_b32_e32 v100, 1, v88
	s_mov_b64 s[20:21], 0x2900000
	s_mov_b32 s37, 0x2900000
	s_mov_b64 s[22:23], 0xb200000
	v_mov_b32_e32 v177, 0x358637bd
	s_mov_b32 s38, 0x800000
	s_mov_b32 s39, 0x2908000
	s_mov_b32 s40, 0x2910000
	s_mov_b32 s41, 0x2918000
	s_mov_b32 s24, s33

;     __device__ __forceinline__ const float* in(int i) const { return karg_in(i); }
; template <bool PASS2>
; __device__ __forceinline__ void s5_tile(const Ctx& C, int T, int sb_lo, int sb_hi, LAS unsigned char* lds, int wave, int lane) {
;     ...
; #pragma unroll
;     for (int gi = 0; gi < 4; ++gi) {
;         const int g = wave * 4 + gi;
;         if (!PASS2) { v2f* Ep = (v2f*)C.E() + ((size_t)T * NG + g) * NP + lane; *Ep = (v2f){sr[gi], si[gi]}; }
; __device__ __forceinline__ void gmlp_tile(const Ctx& C, int T, LAS unsigned char* lds, int wave, int lane, int tid) {
;     ...
;     const bf16* zt = C.Z() + (size_t)(r0 + t) * DIN;
;     const int row = tid >> 2, q = tid & 3;
;     const bf16* vsrc = C.Z() + (size_t)(r0 + row) * DIN + 512 + q * 32;
;     const bf16* Weff = C.Weff();
;     v4u vraw[4];
; #pragma unroll
;     for (int i = 0; i < 4; ++i) vraw[i] = *(const v4u*)(vsrc + 8 * i);
; #pragma unroll
;     for (int h = 0; h < 4; ++h) {
;         bfx8 wf[8];
;         const bf16* wrow = Weff + ((size_t)(mode * 4 + h) * 128 + t) * 128 + 8 * hh;
; #pragma unroll
;         for (int ks = 0; ks < 8; ++ks) wf[ks] = *(const bfx8*)(wrow + 16 * ks);
;         v2u uw[2][4];
; #pragma unroll
;         for (int dbi = 0; dbi < 2; ++dbi)
; #pragma unroll
;             for (int rg = 0; rg < 4; ++rg) uw[dbi][rg] = *(const v2u*)(zt + h * 128 + 32 * (2 * dh + dbi) + 8 * rg + 4 * hh);
;         const float bias = C.in(13)[h * 128 + (mode ? (t & 15) : t)];
;         v4f gvv[8];
;         { const float* gvp = C.in(11) + h * 128 + q * 32;
; #pragma unroll
;           for (int i = 0; i < 8; ++i) gvv[i] = *(const v4f*)(gvp + 4 * i); }
.LBB0_599:
	s_mov_b64 s[0:1], s[80:81]
	s_load_dwordx2 s[0:1], s[0:1], 0x110
	s_lshl_b32 s28, s42, 2
	s_ashr_i32 s25, s24, 31
	s_lshl_b64 s[52:53], s[24:25], 14
	s_ashr_i32 s29, s28, 31
	s_waitcnt lgkmcnt(0)
	s_add_u32 s3, s0, s52
	s_addc_u32 s25, s1, s53
	s_lshl_b64 s[0:1], s[28:29], 9
	s_add_u32 s0, s3, s0
	s_addc_u32 s1, s25, s1
	v_lshlrev_b32_e32 v82, 3, v80
	v_lshl_add_u64 v[0:1], s[0:1], 0, v[82:83]
	v_add_co_u32_e32 v0, vcc, s35, v0
	v_pk_mov_b32 v[2:3], v[166:167], v[166:167] op_sel:[1,0]
	s_nop 0
	v_addc_co_u32_e32 v1, vcc, 0, v1, vcc
	s_mov_b64 s[0:1], s[80:81]
	global_store_dwordx2 v[0:1], v[2:3], off
	s_load_dwordx2 s[0:1], s[0:1], 0x110
	s_or_b32 s54, s28, 1
	s_ashr_i32 s55, s54, 31
	v_pk_mov_b32 v[2:3], v[164:165], v[164:165] op_sel:[1,0]
	v_mov_b32_e32 v97, v83
	s_waitcnt lgkmcnt(0)
	s_add_u32 s3, s0, s52
	s_addc_u32 s25, s1, s53
	s_lshl_b64 s[0:1], s[54:55], 9
	s_add_u32 s0, s3, s0
	s_addc_u32 s1, s25, s1
	v_lshl_add_u64 v[0:1], s[0:1], 0, v[82:83]
	v_add_co_u32_e32 v0, vcc, s35, v0
	s_mov_b64 s[0:1], s[80:81]
	s_nop 0
	v_addc_co_u32_e32 v1, vcc, 0, v1, vcc
	global_store_dwordx2 v[0:1], v[2:3], off
	s_load_dwordx2 s[0:1], s[0:1], 0x110
	s_or_b32 s54, s28, 2
	s_ashr_i32 s55, s54, 31
	v_pk_mov_b32 v[2:3], v[162:163], v[162:163] op_sel:[1,0]
	v_mov_b32_e32 v101, v83
	s_waitcnt lgkmcnt(0)
	s_add_u32 s3, s0, s52
	s_addc_u32 s25, s1, s53
	s_lshl_b64 s[0:1], s[54:55], 9
	s_add_u32 s0, s3, s0
	s_addc_u32 s1, s25, s1
	v_lshl_add_u64 v[0:1], s[0:1], 0, v[82:83]
	v_add_co_u32_e32 v0, vcc, s35, v0
	s_mov_b64 s[0:1], s[80:81]
	s_nop 0
	v_addc_co_u32_e32 v1, vcc, 0, v1, vcc
	global_store_dwordx2 v[0:1], v[2:3], off
	s_load_dwordx2 s[0:1], s[0:1], 0x110
	s_or_b32 s28, s28, 3
	s_ashr_i32 s29, s28, 31
	v_pk_mov_b32 v[2:3], v[160:161], v[160:161] op_sel:[1,0]
	v_lshlrev_b32_e32 v139, 2, v86
	s_waitcnt lgkmcnt(0)
	s_add_u32 s3, s0, s52
	s_addc_u32 s25, s1, s53
	s_lshl_b64 s[0:1], s[28:29], 9
	s_add_u32 s0, s3, s0
	s_addc_u32 s1, s25, s1
	v_lshl_add_u64 v[0:1], s[0:1], 0, v[82:83]
	v_add_co_u32_e32 v0, vcc, s35, v0
	s_mov_b64 s[0:1], s[80:81]
	s_nop 0
	v_addc_co_u32_e32 v1, vcc, 0, v1, vcc
	global_store_dwordx2 v[0:1], v[2:3], off
	s_barrier
	s_mov_b64 s[28:29], s[80:81]
	s_load_dwordx2 s[0:1], s[0:1], 0x110
	s_load_dwordx2 s[28:29], s[28:29], 0x110
	v_add_u32_e32 v2, s26, v173
	v_lshlrev_b32_e32 v82, 1, v86
	s_lshl_b32 s3, s42, 5
	s_and_b32 s3, s3, 0x60
	s_waitcnt lgkmcnt(0)
	v_mov_b64_e32 v[0:1], s[28:29]
	v_mad_i64_i32 v[0:1], s[28:29], v2, s34, v[0:1]
	v_lshl_add_u64 v[0:1], v[0:1], 0, v[82:83]
	v_add_co_u32_e32 v2, vcc, s36, v0
	s_mov_b64 s[28:29], s[80:81]
	s_nop 0
	v_addc_co_u32_e32 v3, vcc, 0, v1, vcc
	global_load_dwordx4 v[8:11], v[2:3], off offset:1024
	v_lshl_add_u64 v[108:109], v[0:1], 0, s[18:19]
	global_load_dwordx4 v[12:15], v[108:109], off offset:16
	global_load_dwordx4 v[16:19], v[108:109], off offset:32
	global_load_dwordx4 v[20:23], v[108:109], off offset:48
	v_or_b32_e32 v132, s3, v85
	v_or_b32_e32 v2, s26, v132
	s_load_dwordx2 s[26:27], s[28:29], 0x110
	v_mov_b64_e32 v[0:1], s[0:1]
	s_ashr_i32 s13, s13, 8
	v_mad_i64_i32 v[0:1], s[0:1], v2, s34, v[0:1]
	s_waitcnt lgkmcnt(0)
	v_lshl_add_u64 v[2:3], s[26:27], 0, v[96:97]
	v_lshlrev_b32_e32 v82, 8, v132
	s_lshl_b32 s26, s13, 6
	v_lshl_add_u64 v[104:105], v[2:3], 0, v[82:83]
	v_bfe_u32 v234, v81, 5, 1
	v_mul_u32_u24_e32 v234, 0x1f0, v234
	v_mul_u32_u24_e32 v235, 0xf0, v85
	v_sub_u32_e32 v234, v234, v235
	v_add_u32_e32 v234, 0xe00, v234
	v_ashrrev_i32_e32 v235, 31, v234
	v_lshl_add_u64 v[104:105], v[234:235], 0, v[104:105]
	v_lshl_add_u64 v[4:5], v[0:1], 0, v[100:101]
	v_add_co_u32_e32 v0, vcc, s37, v104
	s_ashr_i32 s27, s26, 31
	v_lshl_add_u64 v[6:7], v[104:105], 0, s[20:21]
	v_addc_co_u32_e32 v1, vcc, 0, v105, vcc
	v_lshl_add_u64 v[4:5], s[26:27], 1, v[4:5]
	global_load_dwordx4 v[64:67], v[6:7], off offset:-2560
	global_load_dwordx4 v[60:63], v[6:7], off offset:-1536
	global_load_dwordx4 v[56:59], v[6:7], off offset:-512
	global_load_dwordx4 v[48:51], v[6:7], off offset:512
	global_load_dwordx4 v[44:47], v[6:7], off offset:1536
	global_load_dwordx4 v[36:39], v[6:7], off offset:2560
	s_nop 0
	global_load_dwordx4 v[0:3], v[0:1], off offset:-3584
	s_nop 0
	global_load_dwordx4 v[28:31], v[6:7], off offset:3584
	v_add_co_u32_e32 v6, vcc, s36, v4
	v_lshl_add_u64 v[106:107], v[4:5], 0, s[22:23]
	v_bfe_u32 v236, v81, 3, 3
	v_mul_u32_u24_e32 v233, 0x90, v236
	v_sub_u32_e32 v236, v236, v85
	v_mul_i32_i24_e32 v236, 0xc00, v236
	v_and_b32_e32 v237, 7, v81
	v_lshlrev_b32_e32 v237, 4, v237
	v_add_u32_e32 v236, v236, v237
	v_add_u32_e32 v233, v233, v237
	v_bfe_u32 v237, v81, 5, 1
	v_lshlrev_b32_e32 v237, 3, v237
	v_sub_u32_e32 v236, v236, v237
	v_lshrrev_b32_e32 v254, 6, v81
	v_mul_u32_u24_e32 v254, 0x1200, v254
	v_add_u32_e32 v254, 0xa000, v254
	v_mul_u32_u24_e32 v255, 0x90, v85
	v_add3_u32 v255, v255, v237, v254
	v_add_u32_e32 v254, v254, v233
	v_ashrrev_i32_e32 v237, 31, v236
	v_lshl_add_u64 v[236:237], v[106:107], 0, v[236:237]
	s_movk_i32 s98, 0x6000
	s_mov_b32 s99, 0
	s_mov_b32 s100, 0xfffee000
	s_mov_b32 s101, -1
	s_nop 0
	v_addc_co_u32_e32 v7, vcc, 0, v5, vcc
	s_mov_b64 s[0:1], s[80:81]
	global_load_dwordx4 v[238:241], v[236:237], off
	v_lshl_add_u64 v[236:237], v[236:237], 0, s[98:99]
	global_load_dwordx4 v[242:245], v[236:237], off
	v_lshl_add_u64 v[236:237], v[236:237], 0, s[98:99]
	global_load_dwordx4 v[246:249], v[236:237], off
	v_lshl_add_u64 v[236:237], v[236:237], 0, s[98:99]
	global_load_dwordx4 v[250:253], v[236:237], off
	v_lshl_add_u64 v[236:237], v[236:237], 0, s[100:101]
	s_nop 0
	s_nop 0
	s_load_dwordx2 s[0:1], s[0:1], 0x68
	v_lshlrev_b32_e32 v156, 2, v132
	v_or_b32_e32 v157, s26, v85
	s_waitcnt lgkmcnt(0)
; __device__ __forceinline__ float bf_lo(unsigned w) { return __uint_as_float(w << 16); }
; __device__ __forceinline__ float bf_hi(unsigned w) { return __uint_as_float(w & 0xffff0000u); }
; __device__ __forceinline__ bf16 f2bf(float f) { return (bf16)(cvt_pk_nv(f, 0.f) & 0xffffu); }
; __device__ __forceinline__ void gmlp_tile(const Ctx& C, int T, LAS unsigned char* lds, int wave, int lane, int tid) {
;     ...
;         __syncthreads();
;         {
;             float v[32]; float s = 0.f;
; #pragma unroll
;             for (int i = 0; i < 4; ++i) { const v4u w = vraw[i];
;                 v[8 * i + 0] = bf_lo(w.x); v[8 * i + 1] = bf_hi(w.x); v[8 * i + 2] = bf_lo(w.y); v[8 * i + 3] = bf_hi(w.y);
;                 v[8 * i + 4] = bf_lo(w.z); v[8 * i + 5] = bf_hi(w.z); v[8 * i + 6] = bf_lo(w.w); v[8 * i + 7] = bf_hi(w.w); }
;             if (h < 3) {
; #pragma unroll
;                 for (int i = 0; i < 4; ++i) vraw[i] = *(const v4u*)(vsrc + (h + 1) * 128 + 8 * i);
;             }
; #pragma unroll
;             for (int i = 0; i < 32; ++i) s += v[i] * v[i];
;             s += __shfl_xor(s, 1); s += __shfl_xor(s, 2);
;             const float r = rsqrtf(s * (1.f / 128.f) + EPS);
; #pragma unroll
;             for (int i = 0; i < 32; ++i) { v[i] = v[i] * r * gvv[i >> 2][i & 3]; VT[(q * 32 + i) * VT_STRIDE + row] = f2bf(v[i]); }
	global_load_dword v128, v156, s[0:1]
	s_mov_b64 s[0:1], s[80:81]
	s_load_dwordx2 s[28:29], s[0:1], 0x58
	s_waitcnt lgkmcnt(0)
	global_load_dwordx4 v[114:117], v139, s[28:29] offset:48
	global_load_dwordx4 v[118:121], v139, s[28:29] offset:32
	global_load_dwordx4 v[122:125], v139, s[28:29] offset:16
	global_load_dwordx4 v[134:137], v139, s[28:29]
	s_waitcnt vmcnt(20)
	v_and_b32_e32 v97, 0xffff0000, v8
	v_lshlrev_b32_e32 v82, 16, v8
	v_lshlrev_b32_e32 v130, 16, v10
	v_and_b32_e32 v131, 0xffff0000, v10
	v_mul_f32_e32 v10, v97, v97
	v_lshlrev_b32_e32 v101, 16, v9
	v_fmac_f32_e32 v10, v82, v82
	v_and_b32_e32 v129, 0xffff0000, v9
	v_fmac_f32_e32 v10, v101, v101
	v_fmac_f32_e32 v10, v129, v129
	v_fmac_f32_e32 v10, v130, v130
	v_lshlrev_b32_e32 v133, 16, v11
	v_fmac_f32_e32 v10, v131, v131
	v_and_b32_e32 v138, 0xffff0000, v11
	v_fmac_f32_e32 v10, v133, v133
	s_waitcnt vmcnt(19)
	v_lshlrev_b32_e32 v140, 16, v12
	v_fmac_f32_e32 v10, v138, v138
	v_and_b32_e32 v141, 0xffff0000, v12
	v_fmac_f32_e32 v10, v140, v140
	v_lshlrev_b32_e32 v142, 16, v13
	v_fmac_f32_e32 v10, v141, v141
	v_and_b32_e32 v143, 0xffff0000, v13
	v_fmac_f32_e32 v10, v142, v142
	v_lshlrev_b32_e32 v144, 16, v14
	v_fmac_f32_e32 v10, v143, v143
	v_and_b32_e32 v145, 0xffff0000, v14
	v_fmac_f32_e32 v10, v144, v144
	v_lshlrev_b32_e32 v146, 16, v15
	v_fmac_f32_e32 v10, v145, v145
	v_and_b32_e32 v147, 0xffff0000, v15
	v_fmac_f32_e32 v10, v146, v146
	s_waitcnt vmcnt(18)
	v_lshlrev_b32_e32 v148, 16, v16
	v_fmac_f32_e32 v10, v147, v147
	v_and_b32_e32 v149, 0xffff0000, v16
	v_fmac_f32_e32 v10, v148, v148
	v_lshlrev_b32_e32 v150, 16, v17
	v_fmac_f32_e32 v10, v149, v149
	v_and_b32_e32 v151, 0xffff0000, v17
	v_fmac_f32_e32 v10, v150, v150
	v_lshlrev_b32_e32 v152, 16, v18
	v_fmac_f32_e32 v10, v151, v151
	v_and_b32_e32 v153, 0xffff0000, v18
	v_fmac_f32_e32 v10, v152, v152
	v_lshlrev_b32_e32 v154, 16, v19
	v_fmac_f32_e32 v10, v153, v153
	v_and_b32_e32 v155, 0xffff0000, v19
	v_fmac_f32_e32 v10, v154, v154
	s_waitcnt vmcnt(17)
	v_and_b32_e32 v74, 0xffff0000, v20
	v_lshlrev_b32_e32 v75, 16, v20
	v_fmac_f32_e32 v10, v155, v155
	v_pk_mul_f32 v[8:9], v[74:75], v[74:75]
	v_and_b32_e32 v102, 0xffff0000, v21
	v_add_f32_e32 v9, v9, v10
	v_lshlrev_b32_e32 v103, 16, v21
	v_add_f32_e32 v10, v8, v9
	v_pk_mul_f32 v[8:9], v[102:103], v[102:103]
	v_and_b32_e32 v110, 0xffff0000, v22
	v_add_f32_e32 v9, v9, v10
	v_lshlrev_b32_e32 v111, 16, v22
	v_add_f32_e32 v10, v8, v9
	v_pk_mul_f32 v[8:9], v[110:111], v[110:111]
	v_and_b32_e32 v126, 0xffff0000, v23
	v_add_f32_e32 v9, v9, v10
	v_lshlrev_b32_e32 v127, 16, v23
	v_add_f32_e32 v10, v8, v9
	v_pk_mul_f32 v[8:9], v[126:127], v[126:127]
	s_nop 0
	v_add_f32_e32 v9, v9, v10
	v_add_f32_e32 v16, v8, v9
	ds_bpermute_b32 v17, v183, v16
	global_load_dwordx4 v[8:11], v139, s[28:29] offset:112
	global_load_dwordx4 v[12:15], v139, s[28:29] offset:96
	s_waitcnt lgkmcnt(0)
	v_add_f32_e32 v24, v16, v17
	global_load_dwordx4 v[16:19], v139, s[28:29] offset:80
	global_load_dwordx4 v[20:23], v139, s[28:29] offset:64
	ds_bpermute_b32 v25, v184, v24
	s_waitcnt lgkmcnt(0)
	s_barrier
	v_add_f32_e32 v24, v24, v25
	v_fmamk_f32 v24, v24, 0x3c000000, v177
	v_mul_f32_e32 v25, 0x4b800000, v24
	v_cmp_gt_f32_e32 vcc, s38, v24
	s_nop 1
	v_cndmask_b32_e32 v24, v24, v25, vcc
	v_rsq_f32_e32 v158, v24
	global_load_dwordx4 v[24:27], v[108:109], off offset:304
	global_load_dwordx4 v[32:35], v[108:109], off offset:288
	global_load_dwordx4 v[40:43], v[108:109], off offset:272
	global_load_dwordx4 v[52:55], v[108:109], off offset:256
	v_mul_f32_e32 v159, 0x45800000, v158
	v_cndmask_b32_e32 v158, v158, v159, vcc
	v_mul_f32_e32 v82, v158, v82
	s_waitcnt vmcnt(8)
	ds_write_b128 v254, v[238:241]
	ds_write_b128 v254, v[242:245] offset:1152
	ds_write_b128 v254, v[246:249] offset:2304
	ds_write_b128 v254, v[250:253] offset:3456
	s_waitcnt lgkmcnt(0)
	ds_read_b64 v[6:7], v255
	ds_read_b64 v[4:5], v255 offset:16
	ds_read_b64 v[72:73], v255 offset:32
	ds_read_b64 v[70:71], v255 offset:48
	ds_read_b64 v[68:69], v255 offset:64
	ds_read_b64 v[112:113], v255 offset:80
	ds_read_b64 v[78:79], v255 offset:96
	ds_read_b64 v[76:77], v255 offset:112
	s_waitcnt lgkmcnt(0)
	v_mul_f32_e32 v82, v134, v82
	v_cvt_pk_bf16_f32 v82, v82, v83
	ds_write_b16 v174, v82
	v_mul_f32_e32 v82, v158, v97
	v_mul_f32_e32 v82, v135, v82
	v_cvt_pk_bf16_f32 v82, v82, v83
	ds_write_b16 v174, v82 offset:272
	v_mul_f32_e32 v82, v158, v101
	v_mul_f32_e32 v82, v136, v82
	v_cvt_pk_bf16_f32 v82, v82, v83
	ds_write_b16 v174, v82 offset:544
	v_mul_f32_e32 v82, v158, v129
	v_mul_f32_e32 v82, v137, v82
	v_cvt_pk_bf16_f32 v82, v82, v83
	ds_write_b16 v174, v82 offset:816
	v_mul_f32_e32 v82, v158, v130
	v_mul_f32_e32 v82, v122, v82
	v_cvt_pk_bf16_f32 v82, v82, v83
	ds_write_b16 v174, v82 offset:1088
	v_mul_f32_e32 v82, v158, v131
	v_mul_f32_e32 v82, v123, v82
	v_cvt_pk_bf16_f32 v82, v82, v83
	ds_write_b16 v174, v82 offset:1360
	v_mul_f32_e32 v82, v158, v133
	v_mul_f32_e32 v82, v124, v82
	v_cvt_pk_bf16_f32 v82, v82, v83
	ds_write_b16 v174, v82 offset:1632
	v_mul_f32_e32 v82, v158, v138
	v_mul_f32_e32 v82, v125, v82
	v_cvt_pk_bf16_f32 v82, v82, v83
	ds_write_b16 v174, v82 offset:1904
	v_mul_f32_e32 v82, v158, v140
	v_mul_f32_e32 v82, v118, v82
	v_cvt_pk_bf16_f32 v82, v82, v83
	ds_write_b16 v174, v82 offset:2176
	v_mul_f32_e32 v82, v158, v141
	v_mul_f32_e32 v82, v119, v82
	v_cvt_pk_bf16_f32 v82, v82, v83
	ds_write_b16 v174, v82 offset:2448
	v_mul_f32_e32 v82, v158, v142
	v_mul_f32_e32 v82, v120, v82
	v_cvt_pk_bf16_f32 v82, v82, v83
	ds_write_b16 v174, v82 offset:2720
	v_mul_f32_e32 v82, v158, v143
	v_mul_f32_e32 v82, v121, v82
	v_cvt_pk_bf16_f32 v82, v82, v83
	ds_write_b16 v174, v82 offset:2992
	v_mul_f32_e32 v82, v158, v144
	v_mul_f32_e32 v82, v114, v82
	v_cvt_pk_bf16_f32 v82, v82, v83
	ds_write_b16 v174, v82 offset:3264
	v_mul_f32_e32 v82, v158, v145
	v_mul_f32_e32 v82, v115, v82
	v_cvt_pk_bf16_f32 v82, v82, v83
	ds_write_b16 v174, v82 offset:3536
	v_mul_f32_e32 v82, v158, v146
	v_mul_f32_e32 v82, v116, v82
	v_cvt_pk_bf16_f32 v82, v82, v83
	ds_write_b16 v174, v82 offset:3808
	v_mul_f32_e32 v82, v158, v147
	v_mul_f32_e32 v82, v117, v82
	v_cvt_pk_bf16_f32 v82, v82, v83
	ds_write_b16 v174, v82 offset:4080
	v_mul_f32_e32 v82, v158, v148
	s_waitcnt vmcnt(4)
; __device__ __forceinline__ float bf_lo(unsigned w) { return __uint_as_float(w << 16); }
; __device__ __forceinline__ float bf_hi(unsigned w) { return __uint_as_float(w & 0xffff0000u); }
; #define LAS __attribute__((address_space(3)))
; __device__ __forceinline__ unsigned cvt_pk_nv(float lo, float hi) { unsigned r; asm("v_cvt_pk_bf16_f32 %0, %1, %2" : "=v"(r) : "v"(lo), "v"(hi)); return r; }
; __device__ __forceinline__ bf16 f2bf(float f) { return (bf16)(cvt_pk_nv(f, 0.f) & 0xffffu); }
;     __device__ __forceinline__ float* out() const { return (float*)karg_in(33); }
; __device__ __forceinline__ void gmlp_tile(const Ctx& C, int T, LAS unsigned char* lds, int wave, int lane, int tid) {
;     ...
;             for (int i = 0; i < 32; ++i) { v[i] = v[i] * r * gvv[i >> 2][i & 3]; VT[(q * 32 + i) * VT_STRIDE + row] = f2bf(v[i]); }
;             if (mode) { float* ov = C.out() + OFF_V_S + (size_t)row * AW + h * 128 + q * 32;
; #pragma unroll
;                 for (int i = 0; i < 8; ++i) *(v4f*)(ov + 4 * i) = (v4f){v[4 * i], v[4 * i + 1], v[4 * i + 2], v[4 * i + 3]}; }
;         }
;         __syncthreads();
; #pragma unroll
;         for (int dbi = 0; dbi < 2; ++dbi) {
;             const int db = 2 * dh + dbi;
;             v16f acc;
; #pragma unroll
;             for (int r = 0; r < 16; ++r) acc[r] = 0.f;
; #pragma unroll
;             for (int ks = 0; ks < 8; ++ks) {
;                 const bfx8 va = *(const LAS bfx8*)(VT + (32 * db + tl) * VT_STRIDE + 16 * ks + 8 * hh);
;                 acc = __builtin_amdgcn_mfma_f32_32x32x16_bf16(va, wf[ks], acc, 0, 0, 0);
;             }
; #pragma unroll
;             for (int rg = 0; rg < 4; ++rg) {
;                 const v2u u2 = uw[dbi][rg];
;                 const float o0 = bf_lo(u2.x) * (acc[4 * rg + 0] + bias), o1 = bf_hi(u2.x) * (acc[4 * rg + 1] + bias);
;                 const float o2 = bf_lo(u2.y) * (acc[4 * rg + 2] + bias), o3 = bf_hi(u2.y) * (acc[4 * rg + 3] + bias);
;                 ssq += (o0 * o0 + o1 * o1) + (o2 * o2 + o3 * o3);
;                 outp[h][dbi][2 * rg] = cvt_pk_nv(o0, o1); outp[h][dbi][2 * rg + 1] = cvt_pk_nv(o2, o3);
;             }
;         }
	v_mul_f32_e32 v20, v20, v82
	v_cvt_pk_bf16_f32 v20, v20, v83
	ds_write_b16 v174, v20 offset:4352
	v_mul_f32_e32 v20, v158, v149
	v_mul_f32_e32 v20, v21, v20
	v_cvt_pk_bf16_f32 v20, v20, v83
	ds_write_b16 v174, v20 offset:4624
	v_mul_f32_e32 v20, v158, v150
	v_mul_f32_e32 v20, v22, v20
	v_cvt_pk_bf16_f32 v20, v20, v83
	ds_write_b16 v174, v20 offset:4896
	v_mul_f32_e32 v20, v158, v151
	v_mul_f32_e32 v20, v23, v20
	v_cvt_pk_bf16_f32 v20, v20, v83
	ds_write_b16 v174, v20 offset:5168
	v_mul_f32_e32 v20, v158, v152
	v_mul_f32_e32 v16, v16, v20
	v_cvt_pk_bf16_f32 v16, v16, v83
	ds_write_b16 v174, v16 offset:5440
	v_mul_f32_e32 v16, v158, v153
	v_mul_f32_e32 v16, v17, v16
	v_cvt_pk_bf16_f32 v16, v16, v83
	ds_write_b16 v174, v16 offset:5712
	v_mul_f32_e32 v16, v158, v154
	v_mul_f32_e32 v16, v18, v16
	v_cvt_pk_bf16_f32 v16, v16, v83
	ds_write_b16 v174, v16 offset:5984
	v_mul_f32_e32 v16, v158, v155
	v_mul_f32_e32 v16, v19, v16
	v_cvt_pk_bf16_f32 v16, v16, v83
	ds_write_b16 v174, v16 offset:6256
	v_mul_f32_e32 v16, v158, v75
	v_mul_f32_e32 v12, v12, v16
	v_cvt_pk_bf16_f32 v12, v12, v83
	ds_write_b16 v174, v12 offset:6528
	v_mul_f32_e32 v12, v158, v74
	v_mul_f32_e32 v12, v13, v12
	v_cvt_pk_bf16_f32 v12, v12, v83
	ds_write_b16 v174, v12 offset:6800
	v_mul_f32_e32 v12, v158, v103
	v_mul_f32_e32 v12, v14, v12
	v_cvt_pk_bf16_f32 v12, v12, v83
	ds_write_b16 v174, v12 offset:7072
	v_mul_f32_e32 v12, v158, v102
	v_mul_f32_e32 v12, v15, v12
	v_cvt_pk_bf16_f32 v12, v12, v83
	ds_write_b16 v174, v12 offset:7344
	v_mul_f32_e32 v12, v158, v111
	v_mul_f32_e32 v8, v8, v12
	v_cvt_pk_bf16_f32 v8, v8, v83
	ds_write_b16 v174, v8 offset:7616
	v_mul_f32_e32 v8, v158, v110
	v_mul_f32_e32 v8, v9, v8
	v_cvt_pk_bf16_f32 v8, v8, v83
	ds_write_b16 v174, v8 offset:7888
	v_mul_f32_e32 v8, v158, v127
	v_mul_f32_e32 v8, v10, v8
	v_cvt_pk_bf16_f32 v8, v8, v83
	ds_write_b16 v174, v8 offset:8160
	v_mul_f32_e32 v8, v158, v126
	v_mul_f32_e32 v8, v11, v8
	v_cvt_pk_bf16_f32 v8, v8, v83
	v_mad_u64_u32 v[102:103], s[0:1], v157, s30, v[90:91]
	v_lshrrev_b32_e32 v103, 6, v157
	v_lshl_add_u32 v102, v103, 5, v102
	ds_write_b16 v174, v8 offset:8432
	s_waitcnt lgkmcnt(0)
	s_barrier
	ds_read_b128 v[8:11], v102
	ds_read_b128 v[114:117], v102 offset:32
	s_waitcnt lgkmcnt(1)
	v_mfma_f32_32x32x16_bf16 v[8:23], v[8:11], v[0:3], 0
	v_lshlrev_b32_e32 v74, 16, v6
	v_and_b32_e32 v6, 0xffff0000, v6
	s_mov_b64 s[0:1], s[80:81]
	s_waitcnt vmcnt(0)
	v_and_b32_e32 v164, 0xffff0000, v52
	v_lshlrev_b32_e32 v158, 16, v52
	v_lshlrev_b32_e32 v200, 16, v34
	v_and_b32_e32 v201, 0xffff0000, v34
	s_waitcnt lgkmcnt(0)
	v_mfma_f32_32x32x16_bf16 v[8:23], v[114:117], v[64:67], v[8:23]
	ds_read_b128 v[114:117], v102 offset:64
	ds_read_b128 v[118:121], v102 offset:96
	v_mul_f32_e32 v34, v164, v164
	v_lshlrev_b32_e32 v165, 16, v53
	v_fmac_f32_e32 v34, v158, v158
	v_and_b32_e32 v166, 0xffff0000, v53
	v_fmac_f32_e32 v34, v165, v165
	v_lshlrev_b32_e32 v167, 16, v54
	s_waitcnt lgkmcnt(1)
	v_mfma_f32_32x32x16_bf16 v[8:23], v[114:117], v[60:63], v[8:23]
	v_fmac_f32_e32 v34, v166, v166
	v_and_b32_e32 v178, 0xffff0000, v54
	v_fmac_f32_e32 v34, v167, v167
	v_lshlrev_b32_e32 v179, 16, v55
	v_fmac_f32_e32 v34, v178, v178
	v_and_b32_e32 v180, 0xffff0000, v55
	v_fmac_f32_e32 v34, v179, v179
	s_waitcnt lgkmcnt(0)
	v_mfma_f32_32x32x16_bf16 v[8:23], v[118:121], v[56:59], v[8:23]
	ds_read_b128 v[114:117], v102 offset:128
	ds_read_b128 v[118:121], v102 offset:160
	v_lshlrev_b32_e32 v181, 16, v40
	v_fmac_f32_e32 v34, v180, v180
	v_and_b32_e32 v189, 0xffff0000, v40
	v_fmac_f32_e32 v34, v181, v181
	v_lshlrev_b32_e32 v190, 16, v41
	v_fmac_f32_e32 v34, v189, v189
	s_waitcnt lgkmcnt(1)
	v_mfma_f32_32x32x16_bf16 v[8:23], v[114:117], v[48:51], v[8:23]
	v_and_b32_e32 v191, 0xffff0000, v41
	v_fmac_f32_e32 v34, v190, v190
	v_lshlrev_b32_e32 v192, 16, v42
	v_fmac_f32_e32 v34, v191, v191
	v_and_b32_e32 v193, 0xffff0000, v42
	v_fmac_f32_e32 v34, v192, v192
	v_lshlrev_b32_e32 v194, 16, v43
	s_waitcnt lgkmcnt(0)
	v_mfma_f32_32x32x16_bf16 v[8:23], v[118:121], v[44:47], v[8:23]
	ds_read_b128 v[114:117], v102 offset:192
	ds_read_b128 v[118:121], v102 offset:224
	v_fmac_f32_e32 v34, v193, v193
	v_and_b32_e32 v195, 0xffff0000, v43
	v_fmac_f32_e32 v34, v194, v194
	v_lshlrev_b32_e32 v196, 16, v32
	v_fmac_f32_e32 v34, v195, v195
	v_and_b32_e32 v197, 0xffff0000, v32
	s_waitcnt lgkmcnt(1)
	v_mfma_f32_32x32x16_bf16 v[8:23], v[114:117], v[36:39], v[8:23]
	ds_read_b128 v[114:117], v102 offset:8752
	v_fmac_f32_e32 v34, v196, v196
	v_lshlrev_b32_e32 v198, 16, v33
	v_fmac_f32_e32 v34, v197, v197
	v_and_b32_e32 v199, 0xffff0000, v33
	v_fmac_f32_e32 v34, v198, v198
	v_fmac_f32_e32 v34, v199, v199
	s_waitcnt lgkmcnt(1)
	v_mfma_f32_32x32x16_bf16 v[8:23], v[118:121], v[28:31], v[8:23]
	ds_read_b128 v[118:121], v102 offset:8784
	v_fmac_f32_e32 v34, v200, v200
	v_lshlrev_b32_e32 v202, 16, v35
	v_fmac_f32_e32 v34, v201, v201
	v_and_b32_e32 v203, 0xffff0000, v35
	v_fmac_f32_e32 v34, v202, v202
	v_fmac_f32_e32 v34, v203, v203
	s_nop 4
	v_add_f32_e32 v9, v128, v9
	v_mul_f32_e32 v6, v9, v6
	v_lshlrev_b32_e32 v9, 16, v7
	v_add_f32_e32 v10, v128, v10
	v_mul_f32_e32 v9, v10, v9
	v_and_b32_e32 v7, 0xffff0000, v7
	v_add_f32_e32 v10, v128, v11
	v_add_f32_e32 v8, v128, v8
	v_mul_f32_e32 v7, v10, v7
	v_mul_f32_e32 v8, v8, v74
	v_mul_f32_e32 v10, v6, v6
	v_mul_f32_e32 v11, v7, v7
	v_cvt_pk_bf16_f32 v97, v8, v6
	v_cvt_pk_bf16_f32 v82, v9, v7
	v_lshlrev_b32_e32 v6, 16, v4
	v_add_f32_e32 v7, v128, v12
	v_mul_f32_e32 v75, v7, v6
	v_and_b32_e32 v4, 0xffff0000, v4
	v_add_f32_e32 v6, v128, v13
	v_mul_f32_e32 v101, v6, v4
	v_lshlrev_b32_e32 v4, 16, v5
	v_add_f32_e32 v6, v128, v14
	v_fmac_f32_e32 v10, v8, v8
	v_mul_f32_e32 v103, v6, v4
	v_and_b32_e32 v8, 0xffff0000, v5
	ds_read_b128 v[4:7], v102 offset:8720
	v_fmac_f32_e32 v11, v9, v9
	v_add_f32_e32 v9, v128, v15
	v_mul_f32_e32 v110, v9, v8
	v_mul_f32_e32 v8, v101, v101
	v_mul_f32_e32 v9, v110, v110
	v_fmac_f32_e32 v8, v75, v75
	v_fmac_f32_e32 v9, v103, v103
	v_add_f32_e32 v74, v10, v11
	v_add_f32_e32 v111, v8, v9
	s_waitcnt lgkmcnt(0)
; __device__ __forceinline__ float bf_lo(unsigned w) { return __uint_as_float(w << 16); }
; __device__ __forceinline__ float bf_hi(unsigned w) { return __uint_as_float(w & 0xffff0000u); }
; #define LAS __attribute__((address_space(3)))
; __device__ __forceinline__ unsigned cvt_pk_nv(float lo, float hi) { unsigned r; asm("v_cvt_pk_bf16_f32 %0, %1, %2" : "=v"(r) : "v"(lo), "v"(hi)); return r; }
;     __device__ __forceinline__ const float* in(int i) const { return karg_in(i); }
; __device__ __forceinline__ void gmlp_tile(const Ctx& C, int T, LAS unsigned char* lds, int wave, int lane, int tid) {
;     ...
;     for (int h = 0; h < 4; ++h) {
;         bfx8 wf[8];
;         const bf16* wrow = Weff + ((size_t)(mode * 4 + h) * 128 + t) * 128 + 8 * hh;
; #pragma unroll
;         for (int ks = 0; ks < 8; ++ks) wf[ks] = *(const bfx8*)(wrow + 16 * ks);
;         v2u uw[2][4];
; #pragma unroll
;         for (int dbi = 0; dbi < 2; ++dbi)
; #pragma unroll
;             for (int rg = 0; rg < 4; ++rg) uw[dbi][rg] = *(const v2u*)(zt + h * 128 + 32 * (2 * dh + dbi) + 8 * rg + 4 * hh);
;         const float bias = C.in(13)[h * 128 + (mode ? (t & 15) : t)];
;         v4f gvv[8];
;         { const float* gvp = C.in(11) + h * 128 + q * 32;
; #pragma unroll
;           for (int i = 0; i < 8; ++i) gvv[i] = *(const v4f*)(gvp + 4 * i); }
;     ...
; #pragma unroll
;         for (int dbi = 0; dbi < 2; ++dbi) {
;             const int db = 2 * dh + dbi;
;             v16f acc;
; #pragma unroll
;             for (int r = 0; r < 16; ++r) acc[r] = 0.f;
; #pragma unroll
;             for (int ks = 0; ks < 8; ++ks) {
;                 const bfx8 va = *(const LAS bfx8*)(VT + (32 * db + tl) * VT_STRIDE + 16 * ks + 8 * hh);
;                 acc = __builtin_amdgcn_mfma_f32_32x32x16_bf16(va, wf[ks], acc, 0, 0, 0);
;             }
; #pragma unroll
;             for (int rg = 0; rg < 4; ++rg) {
;                 const v2u u2 = uw[dbi][rg];
;                 const float o0 = bf_lo(u2.x) * (acc[4 * rg + 0] + bias), o1 = bf_hi(u2.x) * (acc[4 * rg + 1] + bias);
;                 const float o2 = bf_lo(u2.y) * (acc[4 * rg + 2] + bias), o3 = bf_hi(u2.y) * (acc[4 * rg + 3] + bias);
;                 ssq += (o0 * o0 + o1 * o1) + (o2 * o2 + o3 * o3);
;                 outp[h][dbi][2 * rg] = cvt_pk_nv(o0, o1); outp[h][dbi][2 * rg + 1] = cvt_pk_nv(o2, o3);
;             }
;         }
	v_mfma_f32_32x32x16_bf16 v[0:15], v[4:7], v[0:3], 0
	v_cvt_pk_bf16_f32 v134, v75, v101
	v_lshlrev_b32_e32 v75, 16, v72
	v_add_f32_e32 v16, v128, v16
	v_mul_f32_e32 v75, v16, v75
	v_and_b32_e32 v16, 0xffff0000, v72
	v_add_f32_e32 v17, v128, v17
	v_mul_f32_e32 v72, v17, v16
	v_mfma_f32_32x32x16_bf16 v[0:15], v[114:117], v[64:67], v[0:15]
	ds_read_b128 v[64:67], v102 offset:8816
	v_lshlrev_b32_e32 v16, 16, v73
	v_add_f32_e32 v17, v128, v18
	v_mul_f32_e32 v101, v17, v16
	v_and_b32_e32 v16, 0xffff0000, v73
	v_add_f32_e32 v17, v128, v19
	v_add_f32_e32 v74, v74, v111
	v_mfma_f32_32x32x16_bf16 v[0:15], v[118:121], v[60:63], v[0:15]
	v_mul_f32_e32 v60, v17, v16
	ds_read_b128 v[16:19], v102 offset:8848
	v_mul_f32_e32 v61, v72, v72
	v_mul_f32_e32 v62, v60, v60
	v_fmac_f32_e32 v61, v75, v75
	v_fmac_f32_e32 v62, v101, v101
	v_cvt_pk_bf16_f32 v135, v101, v60
	s_waitcnt lgkmcnt(1)
	v_mfma_f32_32x32x16_bf16 v[0:15], v[64:67], v[56:59], v[0:15]
	v_add_f32_e32 v56, v61, v62
	v_add_f32_e32 v61, v56, v74
	ds_read_b128 v[56:59], v102 offset:8880
	v_lshlrev_b32_e32 v60, 16, v70
	v_cvt_pk_bf16_f32 v133, v103, v110
	v_cvt_pk_bf16_f32 v136, v75, v72
	v_and_b32_e32 v130, 0xffff0000, v25
	s_waitcnt lgkmcnt(1)
	v_mfma_f32_32x32x16_bf16 v[0:15], v[16:19], v[48:51], v[0:15]
	v_add_f32_e32 v16, v128, v20
	v_mul_f32_e32 v48, v16, v60
	v_and_b32_e32 v16, 0xffff0000, v70
	v_add_f32_e32 v17, v128, v21
	v_mul_f32_e32 v49, v17, v16
	ds_read_b128 v[16:19], v102 offset:8912
	v_lshlrev_b32_e32 v20, 16, v71
	s_waitcnt lgkmcnt(1)
	v_mfma_f32_32x32x16_bf16 v[0:15], v[56:59], v[44:47], v[0:15]
	v_add_f32_e32 v21, v128, v22
	v_mul_f32_e32 v44, v21, v20
	v_and_b32_e32 v20, 0xffff0000, v71
	v_add_f32_e32 v21, v128, v23
	v_mul_f32_e32 v45, v21, v20
	ds_read_b128 v[20:23], v102 offset:8944
	v_mul_f32_e32 v46, v49, v49
	s_waitcnt lgkmcnt(1)
	v_mfma_f32_32x32x16_bf16 v[0:15], v[16:19], v[36:39], v[0:15]
	v_lshlrev_b32_e32 v17, 16, v68
	v_mul_f32_e32 v16, v45, v45
	v_fmac_f32_e32 v46, v48, v48
	v_fmac_f32_e32 v16, v44, v44
	v_add_f32_e32 v16, v46, v16
	v_add_f32_e32 v16, v16, v61
	v_cvt_pk_bf16_f32 v138, v48, v49
	s_waitcnt lgkmcnt(0)
	v_mfma_f32_32x32x16_bf16 v[0:15], v[20:23], v[28:31], v[0:15]
	v_cvt_pk_bf16_f32 v137, v44, v45
	v_lshlrev_b32_e32 v131, 16, v25
	v_and_b32_e32 v160, 0xffff0000, v26
	v_lshlrev_b32_e32 v161, 16, v26
	v_and_b32_e32 v162, 0xffff0000, v27
	v_lshlrev_b32_e32 v163, 16, v27
	v_lshlrev_b32_e32 v60, 16, v113
	s_nop 5
	v_add_f32_e32 v0, v128, v0
	v_mul_f32_e32 v0, v0, v17
	v_and_b32_e32 v17, 0xffff0000, v68
	v_add_f32_e32 v1, v128, v1
	v_mul_f32_e32 v1, v1, v17
	v_lshlrev_b32_e32 v17, 16, v69
	v_add_f32_e32 v2, v128, v2
	v_mul_f32_e32 v2, v2, v17
	v_and_b32_e32 v17, 0xffff0000, v69
	v_add_f32_e32 v3, v128, v3
	v_mul_f32_e32 v3, v3, v17
	v_mul_f32_e32 v17, v1, v1
	v_mul_f32_e32 v18, v3, v3
	v_fmac_f32_e32 v17, v0, v0
	v_fmac_f32_e32 v18, v2, v2
	v_add_f32_e32 v17, v17, v18
	v_add_f32_e32 v129, v16, v17
	v_add_co_u32_e32 v16, vcc, s39, v104
	v_cvt_pk_bf16_f32 v103, v0, v1
	v_cvt_pk_bf16_f32 v101, v2, v3
	v_add_f32_e32 v4, v128, v4
	s_nop 0
	v_addc_co_u32_e32 v17, vcc, 0, v105, vcc
	global_load_dwordx4 v[0:3], v[16:17], off offset:-3584
	global_load_dwordx4 v[72:75], v[16:17], off offset:-2560
	global_load_dwordx4 v[68:71], v[16:17], off offset:-1536
	global_load_dwordx4 v[64:67], v[16:17], off offset:-512
	global_load_dwordx4 v[56:59], v[16:17], off offset:512
	global_load_dwordx4 v[48:51], v[16:17], off offset:1536
	global_load_dwordx4 v[44:47], v[16:17], off offset:2560
	global_load_dwordx4 v[36:39], v[16:17], off offset:3584
	global_load_dwordx4 v[238:241], v[236:237], off offset:256
	v_lshl_add_u64 v[236:237], v[236:237], 0, s[98:99]
	global_load_dwordx4 v[242:245], v[236:237], off offset:256
	v_lshl_add_u64 v[236:237], v[236:237], 0, s[98:99]
	global_load_dwordx4 v[246:249], v[236:237], off offset:256
	v_lshl_add_u64 v[236:237], v[236:237], 0, s[98:99]
	global_load_dwordx4 v[250:253], v[236:237], off offset:256
	v_lshl_add_u64 v[236:237], v[236:237], 0, s[100:101]
	s_load_dwordx2 s[0:1], s[0:1], 0x68
	v_lshlrev_b32_e32 v16, 16, v112
	v_mul_f32_e32 v157, v4, v16
	v_and_b32_e32 v4, 0xffff0000, v112
	v_add_f32_e32 v5, v128, v5
	s_waitcnt lgkmcnt(0)
	global_load_dword v159, v156, s[0:1] offset:512
	s_mov_b64 s[0:1], s[80:81]
	s_load_dwordx2 s[28:29], s[0:1], 0x58
	s_waitcnt lgkmcnt(0)
	global_load_dwordx4 v[16:19], v139, s[28:29] offset:560
	global_load_dwordx4 v[20:23], v139, s[28:29] offset:544
	global_load_dwordx4 v[28:31], v139, s[28:29] offset:528
	global_load_dwordx4 v[140:143], v139, s[28:29] offset:512
	v_mul_f32_e32 v112, v5, v4
	v_and_b32_e32 v4, 0xffff0000, v24
	v_lshlrev_b32_e32 v5, 16, v24
	v_pk_mul_f32 v[32:33], v[4:5], v[4:5]
	v_add_f32_e32 v6, v128, v6
	v_add_f32_e32 v24, v33, v34
	v_add_f32_e32 v32, v32, v24
	v_pk_mul_f32 v[24:25], v[130:131], v[130:131]
	v_mul_f32_e32 v204, v6, v60
	v_add_f32_e32 v25, v25, v32
	v_add_f32_e32 v32, v24, v25
	v_pk_mul_f32 v[24:25], v[160:161], v[160:161]
	v_and_b32_e32 v6, 0xffff0000, v113
	v_add_f32_e32 v25, v25, v32
	v_add_f32_e32 v26, v24, v25
	v_pk_mul_f32 v[24:25], v[162:163], v[162:163]
	v_add_f32_e32 v8, v128, v8
	v_add_f32_e32 v25, v25, v26
	v_add_f32_e32 v32, v24, v25
	global_load_dwordx4 v[24:27], v139, s[28:29] offset:624
	global_load_dwordx4 v[144:147], v139, s[28:29] offset:608
	global_load_dwordx4 v[148:151], v139, s[28:29] offset:592
	global_load_dwordx4 v[152:155], v139, s[28:29] offset:576
	ds_bpermute_b32 v33, v183, v32
	s_waitcnt lgkmcnt(0)
	s_barrier
; __device__ __forceinline__ float bf_lo(unsigned w) { return __uint_as_float(w << 16); }
; __device__ __forceinline__ float bf_hi(unsigned w) { return __uint_as_float(w & 0xffff0000u); }
; __device__ __forceinline__ bf16 f2bf(float f) { return (bf16)(cvt_pk_nv(f, 0.f) & 0xffffu); }
; __device__ __forceinline__ void gmlp_tile(const Ctx& C, int T, LAS unsigned char* lds, int wave, int lane, int tid) {
;     ...
;         {
;             float v[32]; float s = 0.f;
; #pragma unroll
;             for (int i = 0; i < 4; ++i) { const v4u w = vraw[i];
;                 v[8 * i + 0] = bf_lo(w.x); v[8 * i + 1] = bf_hi(w.x); v[8 * i + 2] = bf_lo(w.y); v[8 * i + 3] = bf_hi(w.y);
;                 v[8 * i + 4] = bf_lo(w.z); v[8 * i + 5] = bf_hi(w.z); v[8 * i + 6] = bf_lo(w.w); v[8 * i + 7] = bf_hi(w.w); }
;             if (h < 3) {
; #pragma unroll
;                 for (int i = 0; i < 4; ++i) vraw[i] = *(const v4u*)(vsrc + (h + 1) * 128 + 8 * i);
;             }
; #pragma unroll
;             for (int i = 0; i < 32; ++i) s += v[i] * v[i];
;             s += __shfl_xor(s, 1); s += __shfl_xor(s, 2);
;             const float r = rsqrtf(s * (1.f / 128.f) + EPS);
; #pragma unroll
;             for (int i = 0; i < 32; ++i) { v[i] = v[i] * r * gvv[i >> 2][i & 3]; VT[(q * 32 + i) * VT_STRIDE + row] = f2bf(v[i]); }
	s_mov_b64 s[0:1], s[80:81]
	v_add_f32_e32 v32, v32, v33
	ds_bpermute_b32 v33, v184, v32
	s_waitcnt lgkmcnt(0)
	v_add_f32_e32 v32, v32, v33
	v_fmamk_f32 v32, v32, 0x3c000000, v177
	v_mul_f32_e32 v33, 0x4b800000, v32
	v_cmp_gt_f32_e32 vcc, s38, v32
	s_nop 1
	v_cndmask_b32_e32 v32, v32, v33, vcc
	v_rsq_f32_e32 v113, v32
	global_load_dwordx4 v[32:35], v[108:109], off offset:560
	global_load_dwordx4 v[40:43], v[108:109], off offset:544
	global_load_dwordx4 v[52:55], v[108:109], off offset:528
	global_load_dwordx4 v[60:63], v[108:109], off offset:512
	v_mul_f32_e32 v205, 0x45800000, v113
	v_cndmask_b32_e32 v113, v113, v205, vcc
	v_mul_f32_e32 v158, v113, v158
	v_mul_f32_e32 v4, v113, v4
	v_mul_f32_e32 v5, v113, v5
	s_waitcnt vmcnt(8)
	ds_write_b128 v254, v[238:241]
	ds_write_b128 v254, v[242:245] offset:1152
	ds_write_b128 v254, v[246:249] offset:2304
	ds_write_b128 v254, v[250:253] offset:3456
	s_waitcnt lgkmcnt(0)
	ds_read_b64 v[126:127], v255
	ds_read_b64 v[124:125], v255 offset:16
	ds_read_b64 v[122:123], v255 offset:32
	ds_read_b64 v[118:119], v255 offset:48
	ds_read_b64 v[116:117], v255 offset:64
	ds_read_b64 v[120:121], v255 offset:80
	ds_read_b64 v[114:115], v255 offset:96
	ds_read_b64 v[110:111], v255 offset:112
	s_waitcnt lgkmcnt(0)
	v_mul_f32_e32 v140, v140, v158
	v_cvt_pk_bf16_f32 v140, v140, v83
	ds_write_b16 v174, v140
	v_mul_f32_e32 v140, v113, v164
	v_mul_f32_e32 v140, v141, v140
	v_cvt_pk_bf16_f32 v140, v140, v83
	ds_write_b16 v174, v140 offset:272
	v_mul_f32_e32 v140, v113, v165
	v_mul_f32_e32 v140, v142, v140
	v_cvt_pk_bf16_f32 v140, v140, v83
	ds_write_b16 v174, v140 offset:544
	v_mul_f32_e32 v140, v113, v166
	v_mul_f32_e32 v140, v143, v140
	v_cvt_pk_bf16_f32 v140, v140, v83
	ds_write_b16 v174, v140 offset:816
	v_mul_f32_e32 v140, v113, v167
	v_mul_f32_e32 v28, v28, v140
	v_cvt_pk_bf16_f32 v28, v28, v83
	ds_write_b16 v174, v28 offset:1088
	v_mul_f32_e32 v28, v113, v178
	v_mul_f32_e32 v28, v29, v28
	v_cvt_pk_bf16_f32 v28, v28, v83
	ds_write_b16 v174, v28 offset:1360
	v_mul_f32_e32 v28, v113, v179
	v_mul_f32_e32 v28, v30, v28
	v_cvt_pk_bf16_f32 v28, v28, v83
	ds_write_b16 v174, v28 offset:1632
	v_mul_f32_e32 v28, v113, v180
	v_mul_f32_e32 v28, v31, v28
	v_cvt_pk_bf16_f32 v28, v28, v83
	ds_write_b16 v174, v28 offset:1904
	v_mul_f32_e32 v28, v113, v181
	v_mul_f32_e32 v20, v20, v28
	v_cvt_pk_bf16_f32 v20, v20, v83
	ds_write_b16 v174, v20 offset:2176
	v_mul_f32_e32 v20, v113, v189
	v_mul_f32_e32 v20, v21, v20
	v_cvt_pk_bf16_f32 v20, v20, v83
	ds_write_b16 v174, v20 offset:2448
	v_mul_f32_e32 v20, v113, v190
	v_mul_f32_e32 v20, v22, v20
	v_cvt_pk_bf16_f32 v20, v20, v83
	ds_write_b16 v174, v20 offset:2720
	v_mul_f32_e32 v20, v113, v191
	v_mul_f32_e32 v20, v23, v20
	v_cvt_pk_bf16_f32 v20, v20, v83
	ds_write_b16 v174, v20 offset:2992
	v_mul_f32_e32 v20, v113, v192
	v_mul_f32_e32 v16, v16, v20
	v_cvt_pk_bf16_f32 v16, v16, v83
	ds_write_b16 v174, v16 offset:3264
	v_mul_f32_e32 v16, v113, v193
	v_mul_f32_e32 v16, v17, v16
	v_cvt_pk_bf16_f32 v16, v16, v83
	ds_write_b16 v174, v16 offset:3536
	v_mul_f32_e32 v16, v113, v194
	v_mul_f32_e32 v16, v18, v16
	v_cvt_pk_bf16_f32 v16, v16, v83
	ds_write_b16 v174, v16 offset:3808
	v_mul_f32_e32 v16, v113, v195
	v_mul_f32_e32 v16, v19, v16
	v_cvt_pk_bf16_f32 v16, v16, v83
	ds_write_b16 v174, v16 offset:4080
	v_mul_f32_e32 v16, v113, v196
	s_waitcnt vmcnt(4)
	v_mul_f32_e32 v16, v152, v16
	v_cvt_pk_bf16_f32 v16, v16, v83
	ds_write_b16 v174, v16 offset:4352
	v_mul_f32_e32 v16, v113, v197
	v_mul_f32_e32 v16, v153, v16
	v_cvt_pk_bf16_f32 v16, v16, v83
	v_mul_f32_e32 v4, v145, v4
	ds_write_b16 v174, v16 offset:4624
	v_mul_f32_e32 v16, v113, v198
	v_cvt_pk_bf16_f32 v4, v4, v83
	v_mul_f32_e32 v16, v154, v16
	ds_write_b16 v174, v4 offset:6800
	v_mul_f32_e32 v4, v113, v131
	v_cvt_pk_bf16_f32 v16, v16, v83
	v_mul_f32_e32 v4, v146, v4
	ds_write_b16 v174, v16 offset:4896
	v_mul_f32_e32 v16, v113, v199
	v_cvt_pk_bf16_f32 v4, v4, v83
	v_mul_f32_e32 v16, v155, v16
	ds_write_b16 v174, v4 offset:7072
	v_mul_f32_e32 v4, v113, v130
	v_cvt_pk_bf16_f32 v16, v16, v83
	v_mul_f32_e32 v4, v147, v4
	ds_write_b16 v174, v16 offset:5168
	v_mul_f32_e32 v16, v113, v200
	v_cvt_pk_bf16_f32 v4, v4, v83
	v_mul_f32_e32 v16, v148, v16
	ds_write_b16 v174, v4 offset:7344
	v_mul_f32_e32 v4, v113, v161
	v_cvt_pk_bf16_f32 v16, v16, v83
	v_mul_f32_e32 v4, v24, v4
	ds_write_b16 v174, v16 offset:5440
	v_mul_f32_e32 v16, v113, v201
	v_cvt_pk_bf16_f32 v4, v4, v83
	v_mul_f32_e32 v16, v149, v16
	ds_write_b16 v174, v4 offset:7616
	v_mul_f32_e32 v4, v113, v160
	v_cvt_pk_bf16_f32 v16, v16, v83
	v_mul_f32_e32 v4, v25, v4
	ds_write_b16 v174, v16 offset:5712
	v_mul_f32_e32 v16, v113, v202
	v_cvt_pk_bf16_f32 v4, v4, v83
	v_mul_f32_e32 v16, v150, v16
	ds_write_b16 v174, v4 offset:7888
	v_mul_f32_e32 v4, v113, v163
	v_cvt_pk_bf16_f32 v16, v16, v83
	v_mul_f32_e32 v4, v26, v4
	ds_write_b16 v174, v16 offset:5984
	v_mul_f32_e32 v16, v113, v203
	v_cvt_pk_bf16_f32 v4, v4, v83
	v_mul_f32_e32 v16, v151, v16
	ds_write_b16 v174, v4 offset:8160
	v_mul_f32_e32 v4, v113, v162
	v_cvt_pk_bf16_f32 v16, v16, v83
	v_mul_f32_e32 v5, v144, v5
	v_mul_f32_e32 v4, v27, v4
	ds_write_b16 v174, v16 offset:6256
	v_cvt_pk_bf16_f32 v5, v5, v83
	ds_write_b16 v174, v5 offset:6528
	v_cvt_pk_bf16_f32 v4, v4, v83
	ds_write_b16 v174, v4 offset:8432
	s_waitcnt lgkmcnt(0)
	s_barrier
; __device__ __forceinline__ float bf_lo(unsigned w) { return __uint_as_float(w << 16); }
; __device__ __forceinline__ float bf_hi(unsigned w) { return __uint_as_float(w & 0xffff0000u); }
; #define LAS __attribute__((address_space(3)))
; __device__ __forceinline__ unsigned cvt_pk_nv(float lo, float hi) { unsigned r; asm("v_cvt_pk_bf16_f32 %0, %1, %2" : "=v"(r) : "v"(lo), "v"(hi)); return r; }
; __device__ __forceinline__ void gmlp_tile(const Ctx& C, int T, LAS unsigned char* lds, int wave, int lane, int tid) {
;     ...
; #pragma unroll
;         for (int dbi = 0; dbi < 2; ++dbi) {
;             const int db = 2 * dh + dbi;
;             v16f acc;
; #pragma unroll
;             for (int r = 0; r < 16; ++r) acc[r] = 0.f;
; #pragma unroll
;             for (int ks = 0; ks < 8; ++ks) {
;                 const bfx8 va = *(const LAS bfx8*)(VT + (32 * db + tl) * VT_STRIDE + 16 * ks + 8 * hh);
;                 acc = __builtin_amdgcn_mfma_f32_32x32x16_bf16(va, wf[ks], acc, 0, 0, 0);
;             }
; #pragma unroll
;             for (int rg = 0; rg < 4; ++rg) {
;                 const v2u u2 = uw[dbi][rg];
;                 const float o0 = bf_lo(u2.x) * (acc[4 * rg + 0] + bias), o1 = bf_hi(u2.x) * (acc[4 * rg + 1] + bias);
;                 const float o2 = bf_lo(u2.y) * (acc[4 * rg + 2] + bias), o3 = bf_hi(u2.y) * (acc[4 * rg + 3] + bias);
;                 ssq += (o0 * o0 + o1 * o1) + (o2 * o2 + o3 * o3);
;                 outp[h][dbi][2 * rg] = cvt_pk_nv(o0, o1); outp[h][dbi][2 * rg + 1] = cvt_pk_nv(o2, o3);
;             }
;         }
	ds_read_b128 v[16:19], v102
	v_add_f32_e32 v4, v128, v7
	v_mul_f32_e32 v113, v4, v6
	v_mul_f32_e32 v4, v112, v112
	v_mul_f32_e32 v5, v113, v113
	v_fmac_f32_e32 v4, v157, v157
	v_fmac_f32_e32 v5, v204, v204
	v_add_f32_e32 v130, v4, v5
	ds_read_b128 v[4:7], v102 offset:32
	s_waitcnt lgkmcnt(1)
	v_mfma_f32_32x32x16_bf16 v[16:31], v[16:19], v[0:3], 0
	ds_read_b128 v[146:149], v102 offset:64
	v_cvt_pk_bf16_f32 v145, v157, v112
	v_lshlrev_b32_e32 v112, 16, v78
	v_cvt_pk_bf16_f32 v142, v204, v113
	v_mul_f32_e32 v112, v8, v112
	v_and_b32_e32 v8, 0xffff0000, v79
	v_add_f32_e32 v129, v130, v129
	s_waitcnt lgkmcnt(1)
	v_mfma_f32_32x32x16_bf16 v[16:31], v[4:7], v[72:75], v[16:31]
	v_and_b32_e32 v4, 0xffff0000, v78
	v_add_f32_e32 v5, v128, v9
	v_mul_f32_e32 v78, v5, v4
	v_lshlrev_b32_e32 v4, 16, v79
	v_add_f32_e32 v5, v128, v10
	v_mul_f32_e32 v113, v5, v4
	ds_read_b128 v[4:7], v102 offset:96
	s_waitcnt lgkmcnt(1)
	v_mfma_f32_32x32x16_bf16 v[16:31], v[146:149], v[68:71], v[16:31]
	v_add_f32_e32 v9, v128, v11
	v_mul_f32_e32 v79, v9, v8
	ds_read_b128 v[8:11], v102 offset:128
	v_mul_f32_e32 v130, v78, v78
	v_mul_f32_e32 v131, v79, v79
	v_fmac_f32_e32 v130, v112, v112
	v_fmac_f32_e32 v131, v113, v113
	s_waitcnt lgkmcnt(1)
	v_mfma_f32_32x32x16_bf16 v[16:31], v[4:7], v[64:67], v[16:31]
	v_add_f32_e32 v4, v130, v131
	v_add_f32_e32 v129, v4, v129
	ds_read_b128 v[4:7], v102 offset:160
	v_cvt_pk_bf16_f32 v146, v112, v78
	v_lshlrev_b32_e32 v78, 16, v76
	v_cvt_pk_bf16_f32 v143, v113, v79
	s_waitcnt vmcnt(0)
	v_and_b32_e32 v189, 0xffff0000, v60
	s_waitcnt lgkmcnt(1)
	v_mfma_f32_32x32x16_bf16 v[16:31], v[8:11], v[56:59], v[16:31]
	v_add_f32_e32 v8, v128, v12
	v_mul_f32_e32 v12, v8, v78
	v_and_b32_e32 v8, 0xffff0000, v76
	v_add_f32_e32 v9, v128, v13
	v_mul_f32_e32 v13, v9, v8
	ds_read_b128 v[8:11], v102 offset:192
	v_lshlrev_b32_e32 v76, 16, v77
	s_waitcnt lgkmcnt(1)
	v_mfma_f32_32x32x16_bf16 v[16:31], v[4:7], v[48:51], v[16:31]
	v_add_f32_e32 v4, v128, v14
	v_mul_f32_e32 v14, v4, v76
	v_and_b32_e32 v4, 0xffff0000, v77
	v_add_f32_e32 v5, v128, v15
	v_mul_f32_e32 v15, v5, v4
	ds_read_b128 v[4:7], v102 offset:224
	v_mul_f32_e32 v76, v13, v13
	s_waitcnt lgkmcnt(1)
	v_mfma_f32_32x32x16_bf16 v[16:31], v[8:11], v[44:47], v[16:31]
	v_mul_f32_e32 v8, v15, v15
	v_fmac_f32_e32 v76, v12, v12
	v_fmac_f32_e32 v8, v14, v14
	v_add_f32_e32 v8, v76, v8
	v_add_f32_e32 v8, v8, v129
	v_cvt_pk_bf16_f32 v147, v12, v13
	v_cvt_pk_bf16_f32 v144, v14, v15
	s_waitcnt lgkmcnt(0)
	v_mfma_f32_32x32x16_bf16 v[16:31], v[4:7], v[36:39], v[16:31]
	v_lshlrev_b32_e32 v4, 16, v126
	v_lshlrev_b32_e32 v162, 16, v60
	v_lshlrev_b32_e32 v198, 16, v61
	v_and_b32_e32 v199, 0xffff0000, v61
	v_lshlrev_b32_e32 v200, 16, v62
	v_and_b32_e32 v201, 0xffff0000, v62
	v_lshlrev_b32_e32 v202, 16, v63
	s_nop 4
	v_add_f32_e32 v5, v159, v16
	v_mul_f32_e32 v4, v5, v4
	v_and_b32_e32 v5, 0xffff0000, v126
	v_add_f32_e32 v6, v159, v17
	v_mul_f32_e32 v5, v6, v5
	v_lshlrev_b32_e32 v6, 16, v127
	v_add_f32_e32 v7, v159, v18
	v_mul_f32_e32 v6, v7, v6
	v_and_b32_e32 v7, 0xffff0000, v127
	v_add_f32_e32 v9, v159, v19
	v_mul_f32_e32 v7, v9, v7
	v_mul_f32_e32 v9, v5, v5
	v_fmac_f32_e32 v9, v4, v4
	v_cvt_pk_bf16_f32 v141, v4, v5
	v_lshlrev_b32_e32 v4, 16, v124
	v_add_f32_e32 v5, v159, v20
	v_mul_f32_e32 v20, v5, v4
	v_and_b32_e32 v4, 0xffff0000, v124
	v_add_f32_e32 v5, v159, v21
	v_mul_f32_e32 v10, v7, v7
	v_mul_f32_e32 v21, v5, v4
	v_lshlrev_b32_e32 v4, 16, v125
	v_add_f32_e32 v5, v159, v22
	v_fmac_f32_e32 v10, v6, v6
	v_cvt_pk_bf16_f32 v140, v6, v7
	v_mul_f32_e32 v22, v5, v4
	ds_read_b128 v[4:7], v102 offset:8720
	ds_read_b128 v[16:19], v102 offset:8752
	v_add_f32_e32 v9, v9, v10
	v_add_f32_e32 v76, v8, v9
	v_and_b32_e32 v8, 0xffff0000, v125
	v_add_f32_e32 v9, v159, v23
	v_mul_f32_e32 v23, v9, v8
	v_mul_f32_e32 v8, v21, v21
	v_mul_f32_e32 v9, v23, v23
	v_fmac_f32_e32 v8, v20, v20
	v_fmac_f32_e32 v9, v22, v22
	v_add_f32_e32 v77, v8, v9
	s_waitcnt lgkmcnt(1)
	v_mfma_f32_32x32x16_bf16 v[0:15], v[4:7], v[0:3], 0
	v_cvt_pk_bf16_f32 v153, v20, v21
	v_lshlrev_b32_e32 v20, 16, v122
	v_add_f32_e32 v21, v159, v24
	v_cvt_pk_bf16_f32 v150, v22, v23
	v_mul_f32_e32 v24, v21, v20
	ds_read_b128 v[20:23], v102 offset:8784
	v_add_f32_e32 v76, v77, v76
	s_waitcnt lgkmcnt(1)
	v_mfma_f32_32x32x16_bf16 v[0:15], v[16:19], v[72:75], v[0:15]
	v_and_b32_e32 v16, 0xffff0000, v122
	v_add_f32_e32 v17, v159, v25
	v_mul_f32_e32 v25, v17, v16
	v_lshlrev_b32_e32 v16, 16, v123
	v_add_f32_e32 v17, v159, v26
	v_mul_f32_e32 v26, v17, v16
	ds_read_b128 v[16:19], v102 offset:8816
	s_waitcnt lgkmcnt(1)
	v_mfma_f32_32x32x16_bf16 v[0:15], v[20:23], v[68:71], v[0:15]
	v_and_b32_e32 v20, 0xffff0000, v123
	v_add_f32_e32 v21, v159, v27
	v_mul_f32_e32 v27, v21, v20
	ds_read_b128 v[20:23], v102 offset:8848
	v_mul_f32_e32 v68, v25, v25
	v_mul_f32_e32 v69, v27, v27
	v_fmac_f32_e32 v68, v24, v24
	s_waitcnt lgkmcnt(1)
	v_mfma_f32_32x32x16_bf16 v[0:15], v[16:19], v[64:67], v[0:15]
	v_fmac_f32_e32 v69, v26, v26
	v_add_f32_e32 v16, v68, v69
	v_add_f32_e32 v64, v16, v76
	ds_read_b128 v[16:19], v102 offset:8880
	v_cvt_pk_bf16_f32 v154, v24, v25
	v_lshlrev_b32_e32 v24, 16, v118
	v_cvt_pk_bf16_f32 v151, v26, v27
	s_waitcnt lgkmcnt(1)
	v_mfma_f32_32x32x16_bf16 v[0:15], v[20:23], v[56:59], v[0:15]
	v_add_f32_e32 v20, v159, v28
	v_mul_f32_e32 v24, v20, v24
	v_and_b32_e32 v20, 0xffff0000, v118
	v_add_f32_e32 v21, v159, v29
	v_mul_f32_e32 v25, v21, v20
	ds_read_b128 v[20:23], v102 offset:8912
	v_lshlrev_b32_e32 v26, 16, v119
	s_waitcnt lgkmcnt(1)
; __device__ __forceinline__ float bf_lo(unsigned w) { return __uint_as_float(w << 16); }
; __device__ __forceinline__ float bf_hi(unsigned w) { return __uint_as_float(w & 0xffff0000u); }
; __device__ __forceinline__ unsigned cvt_pk_nv(float lo, float hi) { unsigned r; asm("v_cvt_pk_bf16_f32 %0, %1, %2" : "=v"(r) : "v"(lo), "v"(hi)); return r; }
; __device__ __forceinline__ void gmlp_tile(const Ctx& C, int T, LAS unsigned char* lds, int wave, int lane, int tid) {
;     ...
;     for (int h = 0; h < 4; ++h) {
;         bfx8 wf[8];
;         const bf16* wrow = Weff + ((size_t)(mode * 4 + h) * 128 + t) * 128 + 8 * hh;
; #pragma unroll
;         for (int ks = 0; ks < 8; ++ks) wf[ks] = *(const bfx8*)(wrow + 16 * ks);
;         v2u uw[2][4];
; #pragma unroll
;         for (int dbi = 0; dbi < 2; ++dbi)
; #pragma unroll
;             for (int rg = 0; rg < 4; ++rg) uw[dbi][rg] = *(const v2u*)(zt + h * 128 + 32 * (2 * dh + dbi) + 8 * rg + 4 * hh);
;         const float bias = C.in(13)[h * 128 + (mode ? (t & 15) : t)];
;         v4f gvv[8];
;         { const float* gvp = C.in(11) + h * 128 + q * 32;
; #pragma unroll
;           for (int i = 0; i < 8; ++i) gvv[i] = *(const v4f*)(gvp + 4 * i); }
;         __syncthreads();
;         {
;             float v[32]; float s = 0.f;
; #pragma unroll
;             for (int i = 0; i < 4; ++i) { const v4u w = vraw[i];
;                 v[8 * i + 0] = bf_lo(w.x); v[8 * i + 1] = bf_hi(w.x); v[8 * i + 2] = bf_lo(w.y); v[8 * i + 3] = bf_hi(w.y);
;                 v[8 * i + 4] = bf_lo(w.z); v[8 * i + 5] = bf_hi(w.z); v[8 * i + 6] = bf_lo(w.w); v[8 * i + 7] = bf_hi(w.w); }
;             if (h < 3) {
; #pragma unroll
;                 for (int i = 0; i < 4; ++i) vraw[i] = *(const v4u*)(vsrc + (h + 1) * 128 + 8 * i);
;             }
; #pragma unroll
;             for (int i = 0; i < 32; ++i) s += v[i] * v[i];
;     ...
;             for (int rg = 0; rg < 4; ++rg) {
;                 const v2u u2 = uw[dbi][rg];
;                 const float o0 = bf_lo(u2.x) * (acc[4 * rg + 0] + bias), o1 = bf_hi(u2.x) * (acc[4 * rg + 1] + bias);
;                 const float o2 = bf_lo(u2.y) * (acc[4 * rg + 2] + bias), o3 = bf_hi(u2.y) * (acc[4 * rg + 3] + bias);
;                 ssq += (o0 * o0 + o1 * o1) + (o2 * o2 + o3 * o3);
;                 outp[h][dbi][2 * rg] = cvt_pk_nv(o0, o1); outp[h][dbi][2 * rg + 1] = cvt_pk_nv(o2, o3);
;             }
;         }
	v_mfma_f32_32x32x16_bf16 v[0:15], v[16:19], v[48:51], v[0:15]
	v_add_f32_e32 v16, v159, v30
	v_mul_f32_e32 v26, v16, v26
	v_and_b32_e32 v16, 0xffff0000, v119
	v_add_f32_e32 v17, v159, v31
	v_mul_f32_e32 v27, v17, v16
	ds_read_b128 v[16:19], v102 offset:8944
	v_mul_f32_e32 v28, v25, v25
	s_waitcnt lgkmcnt(1)
	v_mfma_f32_32x32x16_bf16 v[0:15], v[20:23], v[44:47], v[0:15]
	v_mul_f32_e32 v20, v27, v27
	v_fmac_f32_e32 v28, v24, v24
	v_fmac_f32_e32 v20, v26, v26
	v_add_f32_e32 v20, v28, v20
	v_add_f32_e32 v20, v20, v64
	v_cvt_pk_bf16_f32 v155, v24, v25
	v_cvt_pk_bf16_f32 v152, v26, v27
	s_waitcnt lgkmcnt(0)
	v_mfma_f32_32x32x16_bf16 v[0:15], v[16:19], v[36:39], v[0:15]
	v_lshlrev_b32_e32 v16, 16, v116
	v_mul_f32_e32 v39, v189, v189
	v_fmac_f32_e32 v39, v162, v162
	v_fmac_f32_e32 v39, v198, v198
	v_fmac_f32_e32 v39, v199, v199
	v_fmac_f32_e32 v39, v200, v200
	v_fmac_f32_e32 v39, v201, v201
	s_nop 4
	v_add_f32_e32 v0, v159, v0
	v_mul_f32_e32 v0, v0, v16
	v_and_b32_e32 v16, 0xffff0000, v116
	v_add_f32_e32 v1, v159, v1
	v_mul_f32_e32 v1, v1, v16
	v_lshlrev_b32_e32 v16, 16, v117
	v_add_f32_e32 v2, v159, v2
	v_mul_f32_e32 v2, v2, v16
	v_and_b32_e32 v16, 0xffff0000, v117
	v_add_f32_e32 v3, v159, v3
	v_mul_f32_e32 v3, v3, v16
	v_mul_f32_e32 v16, v1, v1
	v_mul_f32_e32 v17, v3, v3
	v_fmac_f32_e32 v16, v0, v0
	v_fmac_f32_e32 v17, v2, v2
	v_add_f32_e32 v16, v16, v17
	v_add_f32_e32 v157, v20, v16
	v_add_co_u32_e32 v16, vcc, s40, v104
	v_cvt_pk_bf16_f32 v149, v0, v1
	v_cvt_pk_bf16_f32 v148, v2, v3
	v_add_f32_e32 v4, v159, v4
	s_nop 0
	v_addc_co_u32_e32 v17, vcc, 0, v105, vcc
	global_load_dwordx4 v[0:3], v[16:17], off offset:-3584
	global_load_dwordx4 v[76:79], v[16:17], off offset:-2560
	global_load_dwordx4 v[72:75], v[16:17], off offset:-1536
	global_load_dwordx4 v[68:71], v[16:17], off offset:-512
	global_load_dwordx4 v[64:67], v[16:17], off offset:512
	global_load_dwordx4 v[56:59], v[16:17], off offset:1536
	global_load_dwordx4 v[48:51], v[16:17], off offset:2560
	global_load_dwordx4 v[44:47], v[16:17], off offset:3584
	global_load_dwordx4 v[238:241], v[236:237], off offset:512
	v_lshl_add_u64 v[236:237], v[236:237], 0, s[98:99]
	global_load_dwordx4 v[242:245], v[236:237], off offset:512
	v_lshl_add_u64 v[236:237], v[236:237], 0, s[98:99]
	global_load_dwordx4 v[246:249], v[236:237], off offset:512
	v_lshl_add_u64 v[236:237], v[236:237], 0, s[98:99]
	global_load_dwordx4 v[250:253], v[236:237], off offset:512
	v_lshl_add_u64 v[236:237], v[236:237], 0, s[100:101]
	s_load_dwordx2 s[0:1], s[0:1], 0x68
	v_lshlrev_b32_e32 v16, 16, v120
	v_mul_f32_e32 v158, v4, v16
	v_and_b32_e32 v203, 0xffff0000, v63
	v_fmac_f32_e32 v39, v202, v202
	s_waitcnt lgkmcnt(0)
	global_load_dword v163, v156, s[0:1] offset:1024
	s_mov_b64 s[0:1], s[80:81]
	s_load_dwordx2 s[28:29], s[0:1], 0x58
	s_waitcnt lgkmcnt(0)
	global_load_dwordx4 v[16:19], v139, s[28:29] offset:1072
	global_load_dwordx4 v[20:23], v139, s[28:29] offset:1056
	global_load_dwordx4 v[24:27], v139, s[28:29] offset:1040
	global_load_dwordx4 v[28:31], v139, s[28:29] offset:1024
	v_lshlrev_b32_e32 v204, 16, v52
	v_fmac_f32_e32 v39, v203, v203
	v_and_b32_e32 v205, 0xffff0000, v52
	v_fmac_f32_e32 v39, v204, v204
	v_lshlrev_b32_e32 v206, 16, v53
	v_fmac_f32_e32 v39, v205, v205
	v_and_b32_e32 v207, 0xffff0000, v53
	v_fmac_f32_e32 v39, v206, v206
	v_lshlrev_b32_e32 v208, 16, v54
	v_fmac_f32_e32 v39, v207, v207
	v_and_b32_e32 v209, 0xffff0000, v54
	v_fmac_f32_e32 v39, v208, v208
	v_lshlrev_b32_e32 v210, 16, v55
	v_fmac_f32_e32 v39, v209, v209
	v_and_b32_e32 v211, 0xffff0000, v55
	v_fmac_f32_e32 v39, v210, v210
	v_lshlrev_b32_e32 v212, 16, v40
	v_fmac_f32_e32 v39, v211, v211
	v_and_b32_e32 v213, 0xffff0000, v40
	v_fmac_f32_e32 v39, v212, v212
	v_lshlrev_b32_e32 v214, 16, v41
	v_fmac_f32_e32 v39, v213, v213
	v_and_b32_e32 v215, 0xffff0000, v41
	v_fmac_f32_e32 v39, v214, v214
	v_lshlrev_b32_e32 v216, 16, v42
	v_fmac_f32_e32 v39, v215, v215
	v_and_b32_e32 v217, 0xffff0000, v42
	v_fmac_f32_e32 v39, v216, v216
	v_and_b32_e32 v4, 0xffff0000, v120
	v_add_f32_e32 v5, v159, v5
	v_lshlrev_b32_e32 v218, 16, v43
	v_fmac_f32_e32 v39, v217, v217
	v_mul_f32_e32 v120, v5, v4
	v_and_b32_e32 v219, 0xffff0000, v43
	v_fmac_f32_e32 v39, v218, v218
	v_and_b32_e32 v4, 0xffff0000, v32
	v_lshlrev_b32_e32 v5, 16, v32
	global_load_dwordx4 v[40:43], v139, s[28:29] offset:1136
	global_load_dwordx4 v[164:167], v139, s[28:29] offset:1120
	global_load_dwordx4 v[178:181], v139, s[28:29] offset:1104
	global_load_dwordx4 v[190:193], v139, s[28:29] offset:1088
	v_fmac_f32_e32 v39, v219, v219
	v_pk_mul_f32 v[36:37], v[4:5], v[4:5]
	v_and_b32_e32 v160, 0xffff0000, v33
	v_add_f32_e32 v32, v37, v39
	v_lshlrev_b32_e32 v161, 16, v33
	v_add_f32_e32 v36, v36, v32
	v_pk_mul_f32 v[32:33], v[160:161], v[160:161]
	v_and_b32_e32 v194, 0xffff0000, v34
	v_add_f32_e32 v33, v33, v36
	v_lshlrev_b32_e32 v195, 16, v34
	v_add_f32_e32 v36, v32, v33
	v_pk_mul_f32 v[32:33], v[194:195], v[194:195]
	v_and_b32_e32 v196, 0xffff0000, v35
	v_add_f32_e32 v33, v33, v36
	v_lshlrev_b32_e32 v197, 16, v35
	v_add_f32_e32 v34, v32, v33
	v_pk_mul_f32 v[32:33], v[196:197], v[196:197]
	v_lshlrev_b32_e32 v38, 16, v121
	v_add_f32_e32 v33, v33, v34
	v_add_f32_e32 v32, v32, v33
	ds_bpermute_b32 v33, v183, v32
	v_add_f32_e32 v6, v159, v6
	v_mul_f32_e32 v220, v6, v38
	v_and_b32_e32 v6, 0xffff0000, v121
	s_waitcnt lgkmcnt(0)
	v_add_f32_e32 v32, v32, v33
	ds_bpermute_b32 v33, v184, v32
	s_barrier
; __device__ __forceinline__ float bf_lo(unsigned w) { return __uint_as_float(w << 16); }
; __device__ __forceinline__ float bf_hi(unsigned w) { return __uint_as_float(w & 0xffff0000u); }
; __device__ __forceinline__ bf16 f2bf(float f) { return (bf16)(cvt_pk_nv(f, 0.f) & 0xffffu); }
; __device__ __forceinline__ void gmlp_tile(const Ctx& C, int T, LAS unsigned char* lds, int wave, int lane, int tid) {
;     ...
;         {
;             float v[32]; float s = 0.f;
; #pragma unroll
;             for (int i = 0; i < 4; ++i) { const v4u w = vraw[i];
;                 v[8 * i + 0] = bf_lo(w.x); v[8 * i + 1] = bf_hi(w.x); v[8 * i + 2] = bf_lo(w.y); v[8 * i + 3] = bf_hi(w.y);
;                 v[8 * i + 4] = bf_lo(w.z); v[8 * i + 5] = bf_hi(w.z); v[8 * i + 6] = bf_lo(w.w); v[8 * i + 7] = bf_hi(w.w); }
;             if (h < 3) {
; #pragma unroll
;                 for (int i = 0; i < 4; ++i) vraw[i] = *(const v4u*)(vsrc + (h + 1) * 128 + 8 * i);
;             }
; #pragma unroll
;             for (int i = 0; i < 32; ++i) s += v[i] * v[i];
;             s += __shfl_xor(s, 1); s += __shfl_xor(s, 2);
;             const float r = rsqrtf(s * (1.f / 128.f) + EPS);
; #pragma unroll
;             for (int i = 0; i < 32; ++i) { v[i] = v[i] * r * gvv[i >> 2][i & 3]; VT[(q * 32 + i) * VT_STRIDE + row] = f2bf(v[i]); }
	s_waitcnt lgkmcnt(0)
	v_add_f32_e32 v8, v159, v8
	s_mov_b64 s[0:1], s[80:81]
	v_add_f32_e32 v32, v32, v33
	v_fmamk_f32 v32, v32, 0x3c000000, v177
	v_mul_f32_e32 v33, 0x4b800000, v32
	v_cmp_gt_f32_e32 vcc, s38, v32
	s_nop 1
	v_cndmask_b32_e32 v32, v32, v33, vcc
	v_rsq_f32_e32 v121, v32
	global_load_dwordx4 v[36:39], v[108:109], off offset:768
	global_load_dwordx4 v[52:55], v[108:109], off offset:784
	global_load_dwordx4 v[32:35], v[108:109], off offset:816
	global_load_dwordx4 v[60:63], v[108:109], off offset:800
	v_mul_f32_e32 v108, 0x45800000, v121
	v_cndmask_b32_e32 v108, v121, v108, vcc
	v_mul_f32_e32 v109, v108, v162
	s_waitcnt vmcnt(8)
	ds_write_b128 v254, v[238:241]
	ds_write_b128 v254, v[242:245] offset:1152
	ds_write_b128 v254, v[246:249] offset:2304
	ds_write_b128 v254, v[250:253] offset:3456
	s_waitcnt lgkmcnt(0)
	ds_read_b64 v[130:131], v255
	ds_read_b64 v[128:129], v255 offset:16
	ds_read_b64 v[126:127], v255 offset:32
	ds_read_b64 v[124:125], v255 offset:48
	ds_read_b64 v[122:123], v255 offset:64
	ds_read_b64 v[118:119], v255 offset:80
	ds_read_b64 v[116:117], v255 offset:96
	ds_read_b64 v[112:113], v255 offset:112
	s_waitcnt lgkmcnt(0)
	v_mul_f32_e32 v28, v28, v109
	v_cvt_pk_bf16_f32 v28, v28, v83
	ds_write_b16 v174, v28
	v_mul_f32_e32 v28, v108, v189
	v_mul_f32_e32 v28, v29, v28
	v_cvt_pk_bf16_f32 v28, v28, v83
	ds_write_b16 v174, v28 offset:272
	v_mul_f32_e32 v28, v108, v198
	v_mul_f32_e32 v28, v30, v28
	v_cvt_pk_bf16_f32 v28, v28, v83
	ds_write_b16 v174, v28 offset:544
	v_mul_f32_e32 v28, v108, v199
	v_mul_f32_e32 v28, v31, v28
	v_cvt_pk_bf16_f32 v28, v28, v83
	ds_write_b16 v174, v28 offset:816
	v_mul_f32_e32 v28, v108, v200
	v_mul_f32_e32 v24, v24, v28
	v_cvt_pk_bf16_f32 v24, v24, v83
	ds_write_b16 v174, v24 offset:1088
	v_mul_f32_e32 v24, v108, v201
	v_mul_f32_e32 v24, v25, v24
	v_cvt_pk_bf16_f32 v24, v24, v83
	ds_write_b16 v174, v24 offset:1360
	v_mul_f32_e32 v24, v108, v202
	v_mul_f32_e32 v24, v26, v24
	v_cvt_pk_bf16_f32 v24, v24, v83
	ds_write_b16 v174, v24 offset:1632
	v_mul_f32_e32 v24, v108, v203
	v_mul_f32_e32 v24, v27, v24
	v_cvt_pk_bf16_f32 v24, v24, v83
	ds_write_b16 v174, v24 offset:1904
	v_mul_f32_e32 v24, v108, v204
	v_mul_f32_e32 v20, v20, v24
	v_cvt_pk_bf16_f32 v20, v20, v83
	ds_write_b16 v174, v20 offset:2176
	v_mul_f32_e32 v20, v108, v205
	v_mul_f32_e32 v20, v21, v20
	v_cvt_pk_bf16_f32 v20, v20, v83
	ds_write_b16 v174, v20 offset:2448
	v_mul_f32_e32 v20, v108, v206
	v_mul_f32_e32 v20, v22, v20
	v_cvt_pk_bf16_f32 v20, v20, v83
	ds_write_b16 v174, v20 offset:2720
	v_mul_f32_e32 v20, v108, v207
	v_mul_f32_e32 v20, v23, v20
	v_cvt_pk_bf16_f32 v20, v20, v83
	ds_write_b16 v174, v20 offset:2992
	v_mul_f32_e32 v20, v108, v208
	v_mul_f32_e32 v16, v16, v20
	v_cvt_pk_bf16_f32 v16, v16, v83
	ds_write_b16 v174, v16 offset:3264
	v_mul_f32_e32 v16, v108, v209
	v_mul_f32_e32 v16, v17, v16
	v_cvt_pk_bf16_f32 v16, v16, v83
	ds_write_b16 v174, v16 offset:3536
	v_mul_f32_e32 v16, v108, v210
	v_mul_f32_e32 v16, v18, v16
	v_cvt_pk_bf16_f32 v16, v16, v83
	ds_write_b16 v174, v16 offset:3808
	v_mul_f32_e32 v16, v108, v211
	v_mul_f32_e32 v16, v19, v16
	v_cvt_pk_bf16_f32 v16, v16, v83
	ds_write_b16 v174, v16 offset:4080
	v_mul_f32_e32 v16, v108, v212
	s_waitcnt vmcnt(4)
	v_mul_f32_e32 v16, v190, v16
	v_cvt_pk_bf16_f32 v16, v16, v83
	ds_write_b16 v174, v16 offset:4352
	v_mul_f32_e32 v16, v108, v213
	v_mul_f32_e32 v16, v191, v16
	v_mul_f32_e32 v4, v108, v4
	v_cvt_pk_bf16_f32 v16, v16, v83
	v_mul_f32_e32 v4, v165, v4
	ds_write_b16 v174, v16 offset:4624
	v_mul_f32_e32 v16, v108, v214
	v_cvt_pk_bf16_f32 v4, v4, v83
	v_mul_f32_e32 v16, v192, v16
	ds_write_b16 v174, v4 offset:6800
	v_mul_f32_e32 v4, v108, v161
	v_cvt_pk_bf16_f32 v16, v16, v83
	v_mul_f32_e32 v4, v166, v4
	ds_write_b16 v174, v16 offset:4896
	v_mul_f32_e32 v16, v108, v215
	v_cvt_pk_bf16_f32 v4, v4, v83
	v_mul_f32_e32 v16, v193, v16
	ds_write_b16 v174, v4 offset:7072
	v_mul_f32_e32 v4, v108, v160
	v_cvt_pk_bf16_f32 v16, v16, v83
	v_mul_f32_e32 v4, v167, v4
	ds_write_b16 v174, v16 offset:5168
	v_mul_f32_e32 v16, v108, v216
	v_cvt_pk_bf16_f32 v4, v4, v83
	v_mul_f32_e32 v16, v178, v16
	ds_write_b16 v174, v4 offset:7344
	v_mul_f32_e32 v4, v108, v195
	v_cvt_pk_bf16_f32 v16, v16, v83
	v_mul_f32_e32 v4, v40, v4
	ds_write_b16 v174, v16 offset:5440
	v_mul_f32_e32 v16, v108, v217
	v_cvt_pk_bf16_f32 v4, v4, v83
	v_mul_f32_e32 v16, v179, v16
	ds_write_b16 v174, v4 offset:7616
	v_mul_f32_e32 v4, v108, v194
	v_cvt_pk_bf16_f32 v16, v16, v83
	v_mul_f32_e32 v4, v41, v4
	ds_write_b16 v174, v16 offset:5712
	v_mul_f32_e32 v16, v108, v218
	v_cvt_pk_bf16_f32 v4, v4, v83
	v_mul_f32_e32 v16, v180, v16
	ds_write_b16 v174, v4 offset:7888
	v_mul_f32_e32 v4, v108, v197
	v_cvt_pk_bf16_f32 v16, v16, v83
	v_mul_f32_e32 v4, v42, v4
	ds_write_b16 v174, v16 offset:5984
	v_mul_f32_e32 v16, v108, v219
	v_cvt_pk_bf16_f32 v4, v4, v83
	v_mul_f32_e32 v16, v181, v16
	v_mul_f32_e32 v5, v108, v5
	ds_write_b16 v174, v4 offset:8160
	v_mul_f32_e32 v4, v108, v196
	v_cvt_pk_bf16_f32 v16, v16, v83
	v_mul_f32_e32 v5, v164, v5
	v_mul_f32_e32 v4, v43, v4
	ds_write_b16 v174, v16 offset:6256
	v_cvt_pk_bf16_f32 v5, v5, v83
	ds_write_b16 v174, v5 offset:6528
	v_cvt_pk_bf16_f32 v4, v4, v83
	ds_write_b16 v174, v4 offset:8432
	s_waitcnt lgkmcnt(0)
	s_barrier
; __device__ __forceinline__ float bf_lo(unsigned w) { return __uint_as_float(w << 16); }
; __device__ __forceinline__ float bf_hi(unsigned w) { return __uint_as_float(w & 0xffff0000u); }
; #define LAS __attribute__((address_space(3)))
; __device__ __forceinline__ unsigned cvt_pk_nv(float lo, float hi) { unsigned r; asm("v_cvt_pk_bf16_f32 %0, %1, %2" : "=v"(r) : "v"(lo), "v"(hi)); return r; }
; __device__ __forceinline__ void gmlp_tile(const Ctx& C, int T, LAS unsigned char* lds, int wave, int lane, int tid) {
;     ...
; #pragma unroll
;         for (int dbi = 0; dbi < 2; ++dbi) {
;             const int db = 2 * dh + dbi;
;             v16f acc;
; #pragma unroll
;             for (int r = 0; r < 16; ++r) acc[r] = 0.f;
; #pragma unroll
;             for (int ks = 0; ks < 8; ++ks) {
;                 const bfx8 va = *(const LAS bfx8*)(VT + (32 * db + tl) * VT_STRIDE + 16 * ks + 8 * hh);
;                 acc = __builtin_amdgcn_mfma_f32_32x32x16_bf16(va, wf[ks], acc, 0, 0, 0);
;             }
; #pragma unroll
;             for (int rg = 0; rg < 4; ++rg) {
;                 const v2u u2 = uw[dbi][rg];
;                 const float o0 = bf_lo(u2.x) * (acc[4 * rg + 0] + bias), o1 = bf_hi(u2.x) * (acc[4 * rg + 1] + bias);
;                 const float o2 = bf_lo(u2.y) * (acc[4 * rg + 2] + bias), o3 = bf_hi(u2.y) * (acc[4 * rg + 3] + bias);
;                 ssq += (o0 * o0 + o1 * o1) + (o2 * o2 + o3 * o3);
;                 outp[h][dbi][2 * rg] = cvt_pk_nv(o0, o1); outp[h][dbi][2 * rg + 1] = cvt_pk_nv(o2, o3);
;             }
;         }
	ds_read_b128 v[16:19], v102
	v_add_f32_e32 v4, v159, v7
	v_mul_f32_e32 v40, v4, v6
	v_mul_f32_e32 v4, v120, v120
	v_mul_f32_e32 v5, v40, v40
	v_fmac_f32_e32 v4, v158, v158
	v_fmac_f32_e32 v5, v220, v220
	v_add_f32_e32 v41, v4, v5
	ds_read_b128 v[4:7], v102 offset:32
	s_waitcnt lgkmcnt(1)
	v_mfma_f32_32x32x16_bf16 v[16:31], v[16:19], v[0:3], 0
	v_add_f32_e32 v108, v41, v157
	v_cvt_pk_bf16_f32 v157, v220, v40
	v_lshlrev_b32_e32 v40, 16, v114
	v_mul_f32_e32 v109, v8, v40
	ds_read_b128 v[40:43], v102 offset:64
	v_cvt_pk_bf16_f32 v160, v158, v120
	v_and_b32_e32 v8, 0xffff0000, v115
	s_waitcnt lgkmcnt(1)
	v_mfma_f32_32x32x16_bf16 v[16:31], v[4:7], v[76:79], v[16:31]
	v_and_b32_e32 v4, 0xffff0000, v114
	v_add_f32_e32 v5, v159, v9
	v_mul_f32_e32 v114, v5, v4
	v_lshlrev_b32_e32 v4, 16, v115
	v_add_f32_e32 v5, v159, v10
	v_mul_f32_e32 v120, v5, v4
	ds_read_b128 v[4:7], v102 offset:96
	s_waitcnt lgkmcnt(1)
	v_mfma_f32_32x32x16_bf16 v[16:31], v[40:43], v[72:75], v[16:31]
	v_add_f32_e32 v9, v159, v11
	v_mul_f32_e32 v40, v9, v8
	ds_read_b128 v[8:11], v102 offset:128
	v_mul_f32_e32 v41, v114, v114
	v_mul_f32_e32 v42, v40, v40
	v_fmac_f32_e32 v41, v109, v109
	v_fmac_f32_e32 v42, v120, v120
	s_waitcnt lgkmcnt(1)
	v_mfma_f32_32x32x16_bf16 v[16:31], v[4:7], v[68:71], v[16:31]
	v_add_f32_e32 v4, v41, v42
	v_add_f32_e32 v41, v4, v108
	ds_read_b128 v[4:7], v102 offset:160
	v_cvt_pk_bf16_f32 v158, v120, v40
	v_lshlrev_b32_e32 v40, 16, v110
	v_cvt_pk_bf16_f32 v161, v109, v114
	s_waitcnt vmcnt(3)
	v_and_b32_e32 v212, 0xffff0000, v36
	s_waitcnt lgkmcnt(1)
	v_mfma_f32_32x32x16_bf16 v[16:31], v[8:11], v[64:67], v[16:31]
	v_add_f32_e32 v8, v159, v12
	v_mul_f32_e32 v12, v8, v40
	v_and_b32_e32 v8, 0xffff0000, v110
	v_add_f32_e32 v9, v159, v13
	v_mul_f32_e32 v13, v9, v8
	ds_read_b128 v[8:11], v102 offset:192
	v_lshlrev_b32_e32 v40, 16, v111
	s_waitcnt lgkmcnt(1)
	v_mfma_f32_32x32x16_bf16 v[16:31], v[4:7], v[56:59], v[16:31]
	v_add_f32_e32 v4, v159, v14
	v_mul_f32_e32 v14, v4, v40
	v_and_b32_e32 v4, 0xffff0000, v111
	v_add_f32_e32 v5, v159, v15
	v_mul_f32_e32 v15, v5, v4
	ds_read_b128 v[4:7], v102 offset:224
	v_mul_f32_e32 v40, v13, v13
	s_waitcnt lgkmcnt(1)
	v_mfma_f32_32x32x16_bf16 v[16:31], v[8:11], v[48:51], v[16:31]
	v_mul_f32_e32 v8, v15, v15
	v_fmac_f32_e32 v40, v12, v12
	v_fmac_f32_e32 v8, v14, v14
	v_add_f32_e32 v8, v40, v8
	v_add_f32_e32 v8, v8, v41
	v_cvt_pk_bf16_f32 v162, v12, v13
	v_cvt_pk_bf16_f32 v159, v14, v15
	s_waitcnt lgkmcnt(0)
	v_mfma_f32_32x32x16_bf16 v[16:31], v[4:7], v[44:47], v[16:31]
	v_lshlrev_b32_e32 v4, 16, v130
	v_and_b32_e32 v208, 0xffff0000, v38
	v_lshlrev_b32_e32 v209, 16, v38
	v_lshlrev_b32_e32 v213, 16, v36
	v_mul_f32_e32 v38, v212, v212
	v_lshlrev_b32_e32 v211, 16, v37
	v_fmac_f32_e32 v38, v213, v213
	s_nop 4
	v_add_f32_e32 v5, v163, v16
	v_mul_f32_e32 v4, v5, v4
	v_and_b32_e32 v5, 0xffff0000, v130
	v_add_f32_e32 v6, v163, v17
	v_mul_f32_e32 v5, v6, v5
	v_lshlrev_b32_e32 v6, 16, v131
	v_add_f32_e32 v7, v163, v18
	v_mul_f32_e32 v6, v7, v6
	v_and_b32_e32 v7, 0xffff0000, v131
	v_add_f32_e32 v9, v163, v19
	v_mul_f32_e32 v7, v9, v7
	v_mul_f32_e32 v9, v5, v5
	v_fmac_f32_e32 v9, v4, v4
	v_cvt_pk_bf16_f32 v131, v4, v5
	v_lshlrev_b32_e32 v4, 16, v128
	v_add_f32_e32 v5, v163, v20
	v_mul_f32_e32 v20, v5, v4
	v_and_b32_e32 v4, 0xffff0000, v128
	v_add_f32_e32 v5, v163, v21
	v_mul_f32_e32 v10, v7, v7
	v_mul_f32_e32 v21, v5, v4
	v_lshlrev_b32_e32 v4, 16, v129
	v_add_f32_e32 v5, v163, v22
	v_fmac_f32_e32 v10, v6, v6
	v_cvt_pk_bf16_f32 v130, v6, v7
	v_mul_f32_e32 v22, v5, v4
	ds_read_b128 v[4:7], v102 offset:8720
	ds_read_b128 v[16:19], v102 offset:8752
	v_add_f32_e32 v9, v9, v10
	v_add_f32_e32 v40, v8, v9
	v_and_b32_e32 v8, 0xffff0000, v129
	v_add_f32_e32 v9, v163, v23
	v_mul_f32_e32 v23, v9, v8
	v_mul_f32_e32 v8, v21, v21
	v_mul_f32_e32 v9, v23, v23
	v_fmac_f32_e32 v8, v20, v20
	v_fmac_f32_e32 v9, v22, v22
	v_add_f32_e32 v41, v8, v9
	s_waitcnt lgkmcnt(1)
	v_mfma_f32_32x32x16_bf16 v[0:15], v[4:7], v[0:3], 0
	v_cvt_pk_bf16_f32 v129, v20, v21
	v_lshlrev_b32_e32 v20, 16, v126
	v_add_f32_e32 v21, v163, v24
	v_cvt_pk_bf16_f32 v128, v22, v23
	v_mul_f32_e32 v24, v21, v20
	ds_read_b128 v[20:23], v102 offset:8784
	v_add_f32_e32 v40, v41, v40
	s_waitcnt lgkmcnt(1)
	v_mfma_f32_32x32x16_bf16 v[0:15], v[16:19], v[76:79], v[0:15]
	v_and_b32_e32 v16, 0xffff0000, v126
	v_add_f32_e32 v17, v163, v25
	v_mul_f32_e32 v25, v17, v16
	v_lshlrev_b32_e32 v16, 16, v127
	v_add_f32_e32 v17, v163, v26
	v_mul_f32_e32 v26, v17, v16
	ds_read_b128 v[16:19], v102 offset:8816
	s_waitcnt lgkmcnt(1)
	v_mfma_f32_32x32x16_bf16 v[0:15], v[20:23], v[72:75], v[0:15]
	v_and_b32_e32 v20, 0xffff0000, v127
	v_add_f32_e32 v21, v163, v27
	v_mul_f32_e32 v27, v21, v20
	ds_read_b128 v[20:23], v102 offset:8848
	v_mul_f32_e32 v41, v25, v25
	v_mul_f32_e32 v42, v27, v27
	v_fmac_f32_e32 v41, v24, v24
	s_waitcnt lgkmcnt(1)
	v_mfma_f32_32x32x16_bf16 v[0:15], v[16:19], v[68:71], v[0:15]
	v_fmac_f32_e32 v42, v26, v26
	v_add_f32_e32 v16, v41, v42
	v_add_f32_e32 v40, v16, v40
	ds_read_b128 v[16:19], v102 offset:8880
	v_cvt_pk_bf16_f32 v127, v24, v25
	v_lshlrev_b32_e32 v24, 16, v124
	v_cvt_pk_bf16_f32 v126, v26, v27
	s_waitcnt lgkmcnt(1)
	v_mfma_f32_32x32x16_bf16 v[0:15], v[20:23], v[64:67], v[0:15]
	v_add_f32_e32 v20, v163, v28
	v_mul_f32_e32 v24, v20, v24
	v_and_b32_e32 v20, 0xffff0000, v124
	v_add_f32_e32 v21, v163, v29
	v_mul_f32_e32 v25, v21, v20
	ds_read_b128 v[20:23], v102 offset:8912
	v_lshlrev_b32_e32 v26, 16, v125
	s_waitcnt lgkmcnt(1)
	v_mfma_f32_32x32x16_bf16 v[0:15], v[16:19], v[56:59], v[0:15]
	v_add_f32_e32 v16, v163, v30
	v_mul_f32_e32 v26, v16, v26
	v_and_b32_e32 v16, 0xffff0000, v125
	v_add_f32_e32 v17, v163, v31
	v_mul_f32_e32 v27, v17, v16
	ds_read_b128 v[16:19], v102 offset:8944
	v_mul_f32_e32 v28, v25, v25
	s_waitcnt lgkmcnt(1)
; __device__ __forceinline__ float bf_lo(unsigned w) { return __uint_as_float(w << 16); }
; __device__ __forceinline__ float bf_hi(unsigned w) { return __uint_as_float(w & 0xffff0000u); }
; __device__ __forceinline__ unsigned cvt_pk_nv(float lo, float hi) { unsigned r; asm("v_cvt_pk_bf16_f32 %0, %1, %2" : "=v"(r) : "v"(lo), "v"(hi)); return r; }
; __device__ __forceinline__ void gmlp_tile(const Ctx& C, int T, LAS unsigned char* lds, int wave, int lane, int tid) {
;     ...
;     for (int h = 0; h < 4; ++h) {
;         bfx8 wf[8];
;         const bf16* wrow = Weff + ((size_t)(mode * 4 + h) * 128 + t) * 128 + 8 * hh;
; #pragma unroll
;         for (int ks = 0; ks < 8; ++ks) wf[ks] = *(const bfx8*)(wrow + 16 * ks);
;         v2u uw[2][4];
; #pragma unroll
;         for (int dbi = 0; dbi < 2; ++dbi)
; #pragma unroll
;             for (int rg = 0; rg < 4; ++rg) uw[dbi][rg] = *(const v2u*)(zt + h * 128 + 32 * (2 * dh + dbi) + 8 * rg + 4 * hh);
;         const float bias = C.in(13)[h * 128 + (mode ? (t & 15) : t)];
;         v4f gvv[8];
;         { const float* gvp = C.in(11) + h * 128 + q * 32;
; #pragma unroll
;           for (int i = 0; i < 8; ++i) gvv[i] = *(const v4f*)(gvp + 4 * i); }
;         __syncthreads();
;         {
;             float v[32]; float s = 0.f;
; #pragma unroll
;             for (int i = 0; i < 4; ++i) { const v4u w = vraw[i];
;                 v[8 * i + 0] = bf_lo(w.x); v[8 * i + 1] = bf_hi(w.x); v[8 * i + 2] = bf_lo(w.y); v[8 * i + 3] = bf_hi(w.y);
;                 v[8 * i + 4] = bf_lo(w.z); v[8 * i + 5] = bf_hi(w.z); v[8 * i + 6] = bf_lo(w.w); v[8 * i + 7] = bf_hi(w.w); }
;             if (h < 3) {
; #pragma unroll
;                 for (int i = 0; i < 4; ++i) vraw[i] = *(const v4u*)(vsrc + (h + 1) * 128 + 8 * i);
;             }
; #pragma unroll
;             for (int i = 0; i < 32; ++i) s += v[i] * v[i];
;     ...
;             for (int rg = 0; rg < 4; ++rg) {
;                 const v2u u2 = uw[dbi][rg];
;                 const float o0 = bf_lo(u2.x) * (acc[4 * rg + 0] + bias), o1 = bf_hi(u2.x) * (acc[4 * rg + 1] + bias);
;                 const float o2 = bf_lo(u2.y) * (acc[4 * rg + 2] + bias), o3 = bf_hi(u2.y) * (acc[4 * rg + 3] + bias);
;                 ssq += (o0 * o0 + o1 * o1) + (o2 * o2 + o3 * o3);
;                 outp[h][dbi][2 * rg] = cvt_pk_nv(o0, o1); outp[h][dbi][2 * rg + 1] = cvt_pk_nv(o2, o3);
;             }
;         }
	v_mfma_f32_32x32x16_bf16 v[0:15], v[20:23], v[48:51], v[0:15]
	v_mul_f32_e32 v20, v27, v27
	v_fmac_f32_e32 v28, v24, v24
	v_fmac_f32_e32 v20, v26, v26
	v_add_f32_e32 v20, v28, v20
	v_add_f32_e32 v20, v20, v40
	v_cvt_pk_bf16_f32 v125, v24, v25
	v_cvt_pk_bf16_f32 v124, v26, v27
	s_waitcnt lgkmcnt(0)
	v_mfma_f32_32x32x16_bf16 v[0:15], v[16:19], v[44:47], v[0:15]
	v_lshlrev_b32_e32 v16, 16, v122
	v_and_b32_e32 v210, 0xffff0000, v37
	v_fmac_f32_e32 v38, v211, v211
	v_fmac_f32_e32 v38, v210, v210
	v_fmac_f32_e32 v38, v209, v209
	v_lshlrev_b32_e32 v207, 16, v39
	v_fmac_f32_e32 v38, v208, v208
	s_nop 4
	v_add_f32_e32 v0, v163, v0
	v_mul_f32_e32 v18, v0, v16
	v_and_b32_e32 v0, 0xffff0000, v122
	v_add_f32_e32 v1, v163, v1
	v_mul_f32_e32 v19, v1, v0
	v_lshlrev_b32_e32 v0, 16, v123
	v_add_f32_e32 v1, v163, v2
	v_mul_f32_e32 v21, v1, v0
	v_and_b32_e32 v0, 0xffff0000, v123
	v_add_f32_e32 v1, v163, v3
	v_mul_f32_e32 v22, v1, v0
	v_mul_f32_e32 v0, v19, v19
	v_mul_f32_e32 v1, v22, v22
	v_add_co_u32_e32 v16, vcc, s41, v104
	v_fmac_f32_e32 v0, v18, v18
	v_fmac_f32_e32 v1, v21, v21
	v_addc_co_u32_e32 v17, vcc, 0, v105, vcc
	v_add_f32_e32 v23, v0, v1
	global_load_dwordx4 v[0:3], v[16:17], off offset:-3584
	global_load_dwordx4 v[72:75], v[16:17], off offset:-2560
	global_load_dwordx4 v[68:71], v[16:17], off offset:-1536
	global_load_dwordx4 v[64:67], v[16:17], off offset:-512
	global_load_dwordx4 v[56:59], v[16:17], off offset:512
	global_load_dwordx4 v[48:51], v[16:17], off offset:1536
	global_load_dwordx4 v[44:47], v[16:17], off offset:2560
	global_load_dwordx4 v[40:43], v[16:17], off offset:3584
	global_load_dwordx4 v[238:241], v[236:237], off offset:768
	v_lshl_add_u64 v[236:237], v[236:237], 0, s[98:99]
	global_load_dwordx4 v[242:245], v[236:237], off offset:768
	v_lshl_add_u64 v[236:237], v[236:237], 0, s[98:99]
	global_load_dwordx4 v[246:249], v[236:237], off offset:768
	v_lshl_add_u64 v[236:237], v[236:237], 0, s[98:99]
	global_load_dwordx4 v[250:253], v[236:237], off offset:768
	v_lshl_add_u64 v[236:237], v[236:237], 0, s[100:101]
	s_load_dwordx2 s[0:1], s[0:1], 0x68
	v_lshlrev_b32_e32 v16, 16, v118
	v_add_f32_e32 v4, v163, v4
	v_add_f32_e32 v180, v20, v23
	v_cvt_pk_bf16_f32 v107, v18, v19
	s_waitcnt lgkmcnt(0)
	global_load_dword v156, v156, s[0:1] offset:1536
	s_mov_b64 s[0:1], s[80:81]
	s_load_dwordx2 s[28:29], s[0:1], 0x58
	v_cvt_pk_bf16_f32 v106, v21, v22
	v_mul_f32_e32 v181, v4, v16
	s_waitcnt lgkmcnt(0)
	global_load_dwordx4 v[16:19], v139, s[28:29] offset:1584
	global_load_dwordx4 v[20:23], v139, s[28:29] offset:1568
	global_load_dwordx4 v[24:27], v139, s[28:29] offset:1552
	global_load_dwordx4 v[28:31], v139, s[28:29] offset:1536
	v_and_b32_e32 v206, 0xffff0000, v39
	v_fmac_f32_e32 v38, v207, v207
	s_waitcnt vmcnt(19)
	v_lshlrev_b32_e32 v205, 16, v52
	v_fmac_f32_e32 v38, v206, v206
	v_and_b32_e32 v204, 0xffff0000, v52
	v_fmac_f32_e32 v38, v205, v205
	v_lshlrev_b32_e32 v203, 16, v53
	v_fmac_f32_e32 v38, v204, v204
	v_and_b32_e32 v202, 0xffff0000, v53
	v_fmac_f32_e32 v38, v203, v203
	v_lshlrev_b32_e32 v201, 16, v54
	v_fmac_f32_e32 v38, v202, v202
	v_and_b32_e32 v200, 0xffff0000, v54
	v_fmac_f32_e32 v38, v201, v201
	v_lshlrev_b32_e32 v199, 16, v55
	v_fmac_f32_e32 v38, v200, v200
	v_and_b32_e32 v198, 0xffff0000, v55
	v_fmac_f32_e32 v38, v199, v199
	s_waitcnt vmcnt(17)
	v_lshlrev_b32_e32 v197, 16, v60
	v_fmac_f32_e32 v38, v198, v198
	v_and_b32_e32 v196, 0xffff0000, v60
	v_fmac_f32_e32 v38, v197, v197
	v_lshlrev_b32_e32 v195, 16, v61
	v_fmac_f32_e32 v38, v196, v196
	v_and_b32_e32 v194, 0xffff0000, v61
	v_fmac_f32_e32 v38, v195, v195
	v_lshlrev_b32_e32 v193, 16, v62
	v_fmac_f32_e32 v38, v194, v194
	v_and_b32_e32 v192, 0xffff0000, v62
	v_fmac_f32_e32 v38, v193, v193
	v_lshlrev_b32_e32 v191, 16, v63
	v_fmac_f32_e32 v38, v192, v192
	v_add_f32_e32 v189, v163, v5
	v_and_b32_e32 v190, 0xffff0000, v63
	v_fmac_f32_e32 v38, v191, v191
	v_and_b32_e32 v4, 0xffff0000, v32
	v_lshlrev_b32_e32 v5, 16, v32
	v_fmac_f32_e32 v38, v190, v190
	v_pk_mul_f32 v[36:37], v[4:5], v[4:5]
	v_and_b32_e32 v164, 0xffff0000, v33
	v_add_f32_e32 v32, v37, v38
	v_lshlrev_b32_e32 v165, 16, v33
	v_add_f32_e32 v36, v36, v32
	v_pk_mul_f32 v[32:33], v[164:165], v[164:165]
	v_and_b32_e32 v166, 0xffff0000, v34
	v_add_f32_e32 v33, v33, v36
	v_lshlrev_b32_e32 v167, 16, v34
	v_add_f32_e32 v36, v32, v33
	v_pk_mul_f32 v[32:33], v[166:167], v[166:167]
	v_and_b32_e32 v178, 0xffff0000, v35
	v_add_f32_e32 v33, v33, v36
	v_lshlrev_b32_e32 v179, 16, v35
	v_add_f32_e32 v34, v32, v33
	v_pk_mul_f32 v[32:33], v[178:179], v[178:179]
	v_and_b32_e32 v118, 0xffff0000, v118
	v_add_f32_e32 v33, v33, v34
	v_add_f32_e32 v32, v32, v33
	ds_bpermute_b32 v33, v183, v32
	v_lshlrev_b32_e32 v34, 16, v119
	v_add_f32_e32 v6, v163, v6
	v_mul_f32_e32 v118, v189, v118
	v_mul_f32_e32 v189, v6, v34
	s_waitcnt lgkmcnt(0)
	v_add_f32_e32 v6, v32, v33
	global_load_dwordx4 v[32:35], v139, s[28:29] offset:1616
	global_load_dwordx4 v[36:39], v139, s[28:29] offset:1600
	global_load_dwordx4 v[52:55], v139, s[28:29] offset:1648
	global_load_dwordx4 v[60:63], v139, s[28:29] offset:1632
	ds_bpermute_b32 v214, v184, v6
	s_waitcnt lgkmcnt(0)
	s_barrier
; __device__ __forceinline__ bf16 f2bf(float f) { return (bf16)(cvt_pk_nv(f, 0.f) & 0xffffu); }
; __device__ __forceinline__ void gmlp_tile(const Ctx& C, int T, LAS unsigned char* lds, int wave, int lane, int tid) {
;     ...
;             for (int i = 0; i < 32; ++i) s += v[i] * v[i];
;             s += __shfl_xor(s, 1); s += __shfl_xor(s, 2);
;             const float r = rsqrtf(s * (1.f / 128.f) + EPS);
; #pragma unroll
;             for (int i = 0; i < 32; ++i) { v[i] = v[i] * r * gvv[i >> 2][i & 3]; VT[(q * 32 + i) * VT_STRIDE + row] = f2bf(v[i]); }
	v_and_b32_e32 v119, 0xffff0000, v119
	v_add_f32_e32 v6, v6, v214
	v_fmamk_f32 v6, v6, 0x3c000000, v177
	v_mul_f32_e32 v139, 0x4b800000, v6
	v_cmp_gt_f32_e32 vcc, s38, v6
	v_add_f32_e32 v8, v163, v8
	s_nop 0
	v_cndmask_b32_e32 v6, v6, v139, vcc
	v_rsq_f32_e32 v6, v6
	s_nop 0
	v_mul_f32_e32 v139, 0x45800000, v6
	v_cndmask_b32_e32 v6, v6, v139, vcc
	v_mul_f32_e32 v139, v6, v213
	s_waitcnt vmcnt(4)
	ds_write_b128 v254, v[238:241]
	ds_write_b128 v254, v[242:245] offset:1152
	ds_write_b128 v254, v[246:249] offset:2304
	ds_write_b128 v254, v[250:253] offset:3456
	s_waitcnt lgkmcnt(0)
	ds_read_b64 v[122:123], v255
	ds_read_b64 v[120:121], v255 offset:16
	ds_read_b64 v[114:115], v255 offset:32
	ds_read_b64 v[110:111], v255 offset:48
	ds_read_b64 v[108:109], v255 offset:64
	ds_read_b64 v[104:105], v255 offset:80
	ds_read_b64 v[78:79], v255 offset:96
	ds_read_b64 v[76:77], v255 offset:112
	s_waitcnt lgkmcnt(0)
	v_mul_f32_e32 v28, v28, v139
	v_cvt_pk_bf16_f32 v28, v28, v83
	ds_write_b16 v174, v28
	v_mul_f32_e32 v28, v6, v212
	v_mul_f32_e32 v28, v29, v28
	v_cvt_pk_bf16_f32 v28, v28, v83
	ds_write_b16 v174, v28 offset:272
	v_mul_f32_e32 v28, v6, v211
	v_mul_f32_e32 v28, v30, v28
	v_cvt_pk_bf16_f32 v28, v28, v83
	ds_write_b16 v174, v28 offset:544
	v_mul_f32_e32 v28, v6, v210
	v_mul_f32_e32 v28, v31, v28
	v_cvt_pk_bf16_f32 v28, v28, v83
	ds_write_b16 v174, v28 offset:816
	v_mul_f32_e32 v28, v6, v209
	v_mul_f32_e32 v24, v24, v28
	v_cvt_pk_bf16_f32 v24, v24, v83
	ds_write_b16 v174, v24 offset:1088
	v_mul_f32_e32 v24, v6, v208
	v_mul_f32_e32 v24, v25, v24
	v_cvt_pk_bf16_f32 v24, v24, v83
	ds_write_b16 v174, v24 offset:1360
	v_mul_f32_e32 v24, v6, v207
	v_mul_f32_e32 v24, v26, v24
	v_cvt_pk_bf16_f32 v24, v24, v83
	ds_write_b16 v174, v24 offset:1632
	v_mul_f32_e32 v24, v6, v206
	v_mul_f32_e32 v24, v27, v24
	v_cvt_pk_bf16_f32 v24, v24, v83
	ds_write_b16 v174, v24 offset:1904
	v_mul_f32_e32 v24, v6, v205
	v_mul_f32_e32 v20, v20, v24
	v_cvt_pk_bf16_f32 v20, v20, v83
	ds_write_b16 v174, v20 offset:2176
	v_mul_f32_e32 v20, v6, v204
	v_mul_f32_e32 v20, v21, v20
	v_cvt_pk_bf16_f32 v20, v20, v83
	ds_write_b16 v174, v20 offset:2448
	v_mul_f32_e32 v20, v6, v203
	v_mul_f32_e32 v20, v22, v20
	v_cvt_pk_bf16_f32 v20, v20, v83
	ds_write_b16 v174, v20 offset:2720
	v_mul_f32_e32 v20, v6, v202
	v_mul_f32_e32 v20, v23, v20
	v_cvt_pk_bf16_f32 v20, v20, v83
	ds_write_b16 v174, v20 offset:2992
	v_mul_f32_e32 v20, v6, v201
	v_mul_f32_e32 v16, v16, v20
	v_cvt_pk_bf16_f32 v16, v16, v83
	ds_write_b16 v174, v16 offset:3264
	v_mul_f32_e32 v16, v6, v200
	v_mul_f32_e32 v16, v17, v16
	v_cvt_pk_bf16_f32 v16, v16, v83
	ds_write_b16 v174, v16 offset:3536
	v_mul_f32_e32 v16, v6, v199
	v_mul_f32_e32 v16, v18, v16
	v_cvt_pk_bf16_f32 v16, v16, v83
	ds_write_b16 v174, v16 offset:3808
	v_mul_f32_e32 v16, v6, v198
	v_mul_f32_e32 v16, v19, v16
	v_cvt_pk_bf16_f32 v16, v16, v83
	ds_write_b16 v174, v16 offset:4080
	v_mul_f32_e32 v16, v6, v197
	s_waitcnt vmcnt(2)
	v_mul_f32_e32 v16, v36, v16
	v_cvt_pk_bf16_f32 v16, v16, v83
	ds_write_b16 v174, v16 offset:4352
	v_mul_f32_e32 v16, v6, v196
	v_mul_f32_e32 v16, v37, v16
	v_mul_f32_e32 v4, v6, v4
	v_cvt_pk_bf16_f32 v16, v16, v83
	s_waitcnt vmcnt(0)
	v_mul_f32_e32 v4, v61, v4
	ds_write_b16 v174, v16 offset:4624
	v_mul_f32_e32 v16, v6, v195
	v_cvt_pk_bf16_f32 v4, v4, v83
	v_mul_f32_e32 v16, v38, v16
	ds_write_b16 v174, v4 offset:6800
	v_mul_f32_e32 v4, v6, v165
	v_cvt_pk_bf16_f32 v16, v16, v83
	v_mul_f32_e32 v4, v62, v4
	ds_write_b16 v174, v16 offset:4896
	v_mul_f32_e32 v16, v6, v194
	v_cvt_pk_bf16_f32 v4, v4, v83
	v_mul_f32_e32 v16, v39, v16
	ds_write_b16 v174, v4 offset:7072
	v_mul_f32_e32 v4, v6, v164
	v_cvt_pk_bf16_f32 v16, v16, v83
	v_mul_f32_e32 v4, v63, v4
	ds_write_b16 v174, v16 offset:5168
	v_mul_f32_e32 v16, v6, v193
	v_cvt_pk_bf16_f32 v4, v4, v83
	v_mul_f32_e32 v16, v32, v16
	ds_write_b16 v174, v4 offset:7344
	v_mul_f32_e32 v4, v6, v167
	v_cvt_pk_bf16_f32 v16, v16, v83
	v_mul_f32_e32 v4, v52, v4
	ds_write_b16 v174, v16 offset:5440
	v_mul_f32_e32 v16, v6, v192
	v_cvt_pk_bf16_f32 v4, v4, v83
	v_mul_f32_e32 v16, v33, v16
	ds_write_b16 v174, v4 offset:7616
	v_mul_f32_e32 v4, v6, v166
	v_cvt_pk_bf16_f32 v16, v16, v83
	v_mul_f32_e32 v4, v53, v4
	ds_write_b16 v174, v16 offset:5712
	v_mul_f32_e32 v16, v6, v191
	v_cvt_pk_bf16_f32 v4, v4, v83
	v_mul_f32_e32 v16, v34, v16
	ds_write_b16 v174, v4 offset:7888
	v_mul_f32_e32 v4, v6, v179
	v_cvt_pk_bf16_f32 v16, v16, v83
	v_mul_f32_e32 v4, v54, v4
	ds_write_b16 v174, v16 offset:5984
	v_mul_f32_e32 v16, v6, v190
	v_cvt_pk_bf16_f32 v4, v4, v83
	v_mul_f32_e32 v16, v35, v16
	v_mul_f32_e32 v5, v6, v5
	ds_write_b16 v174, v4 offset:8160
	v_mul_f32_e32 v4, v6, v178
	v_cvt_pk_bf16_f32 v16, v16, v83
	v_mul_f32_e32 v5, v60, v5
	v_mul_f32_e32 v4, v55, v4
	ds_write_b16 v174, v16 offset:6256
	v_cvt_pk_bf16_f32 v5, v5, v83
	ds_write_b16 v174, v5 offset:6528
	v_cvt_pk_bf16_f32 v4, v4, v83
	ds_write_b16 v174, v4 offset:8432
	s_waitcnt lgkmcnt(0)
	s_barrier
; __device__ __forceinline__ float bf_lo(unsigned w) { return __uint_as_float(w << 16); }
; __device__ __forceinline__ float bf_hi(unsigned w) { return __uint_as_float(w & 0xffff0000u); }
; #define LAS __attribute__((address_space(3)))
; __device__ __forceinline__ unsigned cvt_pk_nv(float lo, float hi) { unsigned r; asm("v_cvt_pk_bf16_f32 %0, %1, %2" : "=v"(r) : "v"(lo), "v"(hi)); return r; }
; __device__ __forceinline__ void gmlp_tile(const Ctx& C, int T, LAS unsigned char* lds, int wave, int lane, int tid) {
;     ...
; #pragma unroll
;         for (int dbi = 0; dbi < 2; ++dbi) {
;             const int db = 2 * dh + dbi;
;             v16f acc;
; #pragma unroll
;             for (int r = 0; r < 16; ++r) acc[r] = 0.f;
; #pragma unroll
;             for (int ks = 0; ks < 8; ++ks) {
;                 const bfx8 va = *(const LAS bfx8*)(VT + (32 * db + tl) * VT_STRIDE + 16 * ks + 8 * hh);
;                 acc = __builtin_amdgcn_mfma_f32_32x32x16_bf16(va, wf[ks], acc, 0, 0, 0);
;             }
; #pragma unroll
;             for (int rg = 0; rg < 4; ++rg) {
;                 const v2u u2 = uw[dbi][rg];
;                 const float o0 = bf_lo(u2.x) * (acc[4 * rg + 0] + bias), o1 = bf_hi(u2.x) * (acc[4 * rg + 1] + bias);
;                 const float o2 = bf_lo(u2.y) * (acc[4 * rg + 2] + bias), o3 = bf_hi(u2.y) * (acc[4 * rg + 3] + bias);
;                 ssq += (o0 * o0 + o1 * o1) + (o2 * o2 + o3 * o3);
;                 outp[h][dbi][2 * rg] = cvt_pk_nv(o0, o1); outp[h][dbi][2 * rg + 1] = cvt_pk_nv(o2, o3);
;             }
;         }
	ds_read_b128 v[16:19], v102
	v_add_f32_e32 v4, v163, v7
	v_mul_f32_e32 v32, v4, v119
	v_mul_f32_e32 v4, v118, v118
	v_mul_f32_e32 v5, v32, v32
	v_fmac_f32_e32 v4, v181, v181
	v_fmac_f32_e32 v5, v189, v189
	v_add_f32_e32 v33, v4, v5
	ds_read_b128 v[4:7], v102 offset:32
	s_waitcnt lgkmcnt(1)
	v_mfma_f32_32x32x16_bf16 v[16:31], v[16:19], v[0:3], 0
	ds_read_b128 v[36:39], v102 offset:64
	v_lshlrev_b32_e32 v34, 16, v116
	v_mul_f32_e32 v34, v8, v34
	v_and_b32_e32 v8, 0xffff0000, v117
	v_add_f32_e32 v33, v33, v180
	ds_read_b128 v[60:63], v102 offset:8784
	v_cvt_pk_bf16_f32 v35, v181, v118
	s_waitcnt lgkmcnt(2)
	v_mfma_f32_32x32x16_bf16 v[16:31], v[4:7], v[72:75], v[16:31]
	v_and_b32_e32 v4, 0xffff0000, v116
	v_add_f32_e32 v5, v163, v9
	v_mul_f32_e32 v52, v5, v4
	v_lshlrev_b32_e32 v4, 16, v117
	v_add_f32_e32 v5, v163, v10
	v_mul_f32_e32 v53, v5, v4
	ds_read_b128 v[4:7], v102 offset:96
	s_waitcnt lgkmcnt(2)
	v_mfma_f32_32x32x16_bf16 v[16:31], v[36:39], v[68:71], v[16:31]
	v_add_f32_e32 v9, v163, v11
	v_mul_f32_e32 v37, v9, v8
	ds_read_b128 v[8:11], v102 offset:128
	v_mul_f32_e32 v36, v52, v52
	v_mul_f32_e32 v38, v37, v37
	v_fmac_f32_e32 v36, v34, v34
	v_fmac_f32_e32 v38, v53, v53
	s_waitcnt lgkmcnt(1)
	v_mfma_f32_32x32x16_bf16 v[16:31], v[4:7], v[64:67], v[16:31]
	v_add_f32_e32 v4, v36, v38
	v_add_f32_e32 v38, v4, v33
	ds_read_b128 v[4:7], v102 offset:160
	v_cvt_pk_bf16_f32 v36, v34, v52
	v_lshlrev_b32_e32 v34, 16, v112
	v_cvt_pk_bf16_f32 v33, v53, v37
	ds_read_b128 v[52:55], v102 offset:8752
	s_waitcnt lgkmcnt(2)
	v_mfma_f32_32x32x16_bf16 v[16:31], v[8:11], v[56:59], v[16:31]
	v_add_f32_e32 v8, v163, v12
	v_mul_f32_e32 v12, v8, v34
	v_and_b32_e32 v8, 0xffff0000, v112
	v_add_f32_e32 v9, v163, v13
	v_mul_f32_e32 v13, v9, v8
	ds_read_b128 v[8:11], v102 offset:192
	v_lshlrev_b32_e32 v34, 16, v113
	s_waitcnt lgkmcnt(2)
	v_mfma_f32_32x32x16_bf16 v[16:31], v[4:7], v[48:51], v[16:31]
	v_add_f32_e32 v4, v163, v14
	v_mul_f32_e32 v14, v4, v34
	v_and_b32_e32 v4, 0xffff0000, v113
	v_add_f32_e32 v5, v163, v15
	v_mul_f32_e32 v15, v5, v4
	ds_read_b128 v[4:7], v102 offset:224
	v_mul_f32_e32 v34, v13, v13
	s_waitcnt lgkmcnt(1)
	v_mfma_f32_32x32x16_bf16 v[16:31], v[8:11], v[44:47], v[16:31]
	v_mul_f32_e32 v8, v15, v15
	v_fmac_f32_e32 v34, v12, v12
	v_fmac_f32_e32 v8, v14, v14
	v_add_f32_e32 v8, v34, v8
	v_add_f32_e32 v8, v8, v38
	v_cvt_pk_bf16_f32 v37, v12, v13
	v_cvt_pk_bf16_f32 v34, v14, v15
	s_waitcnt lgkmcnt(0)
	v_mfma_f32_32x32x16_bf16 v[16:31], v[4:7], v[40:43], v[16:31]
	v_lshlrev_b32_e32 v4, 16, v122
	v_and_b32_e32 v39, 0xffff0000, v115
	v_cvt_pk_bf16_f32 v32, v189, v32
	s_nop 9
	v_add_f32_e32 v5, v156, v16
	v_mul_f32_e32 v4, v5, v4
	v_and_b32_e32 v5, 0xffff0000, v122
	v_add_f32_e32 v6, v156, v17
	v_mul_f32_e32 v5, v6, v5
	v_lshlrev_b32_e32 v6, 16, v123
	v_add_f32_e32 v7, v156, v18
	v_mul_f32_e32 v6, v7, v6
	v_and_b32_e32 v7, 0xffff0000, v123
	v_add_f32_e32 v9, v156, v19
	v_mul_f32_e32 v7, v9, v7
	v_mul_f32_e32 v9, v5, v5
	v_fmac_f32_e32 v9, v4, v4
	v_cvt_pk_bf16_f32 v17, v4, v5
	v_lshlrev_b32_e32 v4, 16, v120
	v_add_f32_e32 v5, v156, v20
	v_mul_f32_e32 v19, v5, v4
	v_and_b32_e32 v4, 0xffff0000, v120
	v_add_f32_e32 v5, v156, v21
	v_mul_f32_e32 v10, v7, v7
	v_mul_f32_e32 v20, v5, v4
	v_lshlrev_b32_e32 v4, 16, v121
	v_add_f32_e32 v5, v156, v22
	v_fmac_f32_e32 v10, v6, v6
	v_cvt_pk_bf16_f32 v16, v6, v7
	v_mul_f32_e32 v21, v5, v4
	ds_read_b128 v[4:7], v102 offset:8720
	v_add_f32_e32 v9, v9, v10
	v_add_f32_e32 v18, v8, v9
	v_and_b32_e32 v8, 0xffff0000, v121
	v_add_f32_e32 v9, v156, v23
	v_mul_f32_e32 v22, v9, v8
	v_mul_f32_e32 v8, v20, v20
	v_mul_f32_e32 v9, v22, v22
	v_fmac_f32_e32 v8, v19, v19
	v_fmac_f32_e32 v9, v21, v21
	v_add_f32_e32 v23, v8, v9
	s_waitcnt lgkmcnt(0)
	v_mfma_f32_32x32x16_bf16 v[0:15], v[4:7], v[0:3], 0
	v_add_f32_e32 v38, v23, v18
	v_cvt_pk_bf16_f32 v20, v19, v20
	v_cvt_pk_bf16_f32 v18, v21, v22
	v_lshlrev_b32_e32 v19, 16, v114
	v_add_f32_e32 v21, v156, v24
	v_mul_f32_e32 v19, v21, v19
	v_and_b32_e32 v21, 0xffff0000, v114
	v_mfma_f32_32x32x16_bf16 v[0:15], v[52:55], v[72:75], v[0:15]
	v_add_f32_e32 v22, v156, v25
	v_mul_f32_e32 v21, v22, v21
	v_lshlrev_b32_e32 v22, 16, v115
	v_add_f32_e32 v23, v156, v26
	v_mul_f32_e32 v26, v23, v22
	ds_read_b128 v[22:25], v102 offset:8816
	ds_read_b128 v[52:55], v102 offset:8848
	v_mfma_f32_32x32x16_bf16 v[0:15], v[60:63], v[68:71], v[0:15]
	v_add_f32_e32 v27, v156, v27
	v_mul_f32_e32 v27, v27, v39
	v_mul_f32_e32 v39, v21, v21
	v_mul_f32_e32 v60, v27, v27
	v_fmac_f32_e32 v39, v19, v19
	v_fmac_f32_e32 v60, v26, v26
	v_cvt_pk_bf16_f32 v21, v19, v21
	s_waitcnt lgkmcnt(1)
	v_mfma_f32_32x32x16_bf16 v[0:15], v[22:25], v[64:67], v[0:15]
	v_add_f32_e32 v22, v39, v60
	v_add_f32_e32 v38, v22, v38
	ds_read_b128 v[22:25], v102 offset:8880
	v_cvt_pk_bf16_f32 v19, v26, v27
	v_lshlrev_b32_e32 v26, 16, v110
	v_add_f32_e32 v27, v156, v28
	v_mul_f32_e32 v39, v27, v26
	s_waitcnt lgkmcnt(1)
	v_mfma_f32_32x32x16_bf16 v[0:15], v[52:55], v[56:59], v[0:15]
	v_and_b32_e32 v26, 0xffff0000, v110
	v_add_f32_e32 v27, v156, v29
	v_mul_f32_e32 v52, v27, v26
	ds_read_b128 v[26:29], v102 offset:8912
	v_lshlrev_b32_e32 v53, 16, v111
	s_waitcnt lgkmcnt(1)
	v_mfma_f32_32x32x16_bf16 v[0:15], v[22:25], v[48:51], v[0:15]
	ds_read_b128 v[48:51], v102 offset:8944
	v_and_b32_e32 v23, 0xffff0000, v111
	v_add_f32_e32 v24, v156, v31
	v_add_f32_e32 v22, v156, v30
	v_mul_f32_e32 v24, v24, v23
	v_mul_f32_e32 v22, v22, v53
	v_mul_f32_e32 v25, v24, v24
	s_waitcnt lgkmcnt(1)
	v_mfma_f32_32x32x16_bf16 v[0:15], v[26:29], v[44:47], v[0:15]
	v_fmac_f32_e32 v25, v22, v22
	v_cvt_pk_bf16_f32 v22, v22, v24
	v_lshlrev_b32_e32 v24, 16, v108
	v_mul_f32_e32 v23, v52, v52
	v_fmac_f32_e32 v23, v39, v39
	v_add_f32_e32 v23, v23, v25
	v_add_f32_e32 v25, v23, v38
	s_waitcnt lgkmcnt(0)
; __device__ __forceinline__ float bf_lo(unsigned w) { return __uint_as_float(w << 16); }
; __device__ __forceinline__ float bf_hi(unsigned w) { return __uint_as_float(w & 0xffff0000u); }
; #define LAS __attribute__((address_space(3)))
; __device__ __forceinline__ unsigned cvt_pk_nv(float lo, float hi) { unsigned r; asm("v_cvt_pk_bf16_f32 %0, %1, %2" : "=v"(r) : "v"(lo), "v"(hi)); return r; }
;     __device__ __forceinline__ const float* in(int i) const { return karg_in(i); }
; __device__ __forceinline__ void gmlp_tile(const Ctx& C, int T, LAS unsigned char* lds, int wave, int lane, int tid) {
;     ...
;             for (int rg = 0; rg < 4; ++rg) {
;                 const v2u u2 = uw[dbi][rg];
;                 const float o0 = bf_lo(u2.x) * (acc[4 * rg + 0] + bias), o1 = bf_hi(u2.x) * (acc[4 * rg + 1] + bias);
;                 const float o2 = bf_lo(u2.y) * (acc[4 * rg + 2] + bias), o3 = bf_hi(u2.y) * (acc[4 * rg + 3] + bias);
;                 ssq += (o0 * o0 + o1 * o1) + (o2 * o2 + o3 * o3);
;                 outp[h][dbi][2 * rg] = cvt_pk_nv(o0, o1); outp[h][dbi][2 * rg + 1] = cvt_pk_nv(o2, o3);
;             }
;         }
;     }
;     ssq += __shfl_xor(ssq, 32);
;     if (hh == 0) SSQ[t * 2 + dh] = ssq;
;     __syncthreads();
;     const float rstd = rsqrtf((SSQ[t * 2] + SSQ[t * 2 + 1]) * (1.f / 512.f) + EPS);
;     const float* gap = C.in(24);
;     LAS bf16* OT = (LAS bf16*)lds;
;     __syncthreads();
; #pragma unroll
;     for (int h = 0; h < 4; ++h)
; #pragma unroll
;         for (int dbi = 0; dbi < 2; ++dbi)
; #pragma unroll
;             for (int rg = 0; rg < 4; ++rg) {
;                 const int c = h * 128 + 32 * (2 * dh + dbi) + 8 * rg + 4 * hh;
;                 const v4f ga = *(const v4f*)(gap + c);
;                 const unsigned w0 = outp[h][dbi][2 * rg], w1 = outp[h][dbi][2 * rg + 1];
;                 v2u o; o.x = cvt_pk_nv(bf_lo(w0) * rstd * ga.x, bf_hi(w0) * rstd * ga.y); o.y = cvt_pk_nv(bf_lo(w1) * rstd * ga.z, bf_hi(w1) * rstd * ga.w);
;                 *(LAS v2u*)(OT + t * OT_STRIDE + c) = o;
;             }
	v_mfma_f32_32x32x16_bf16 v[0:15], v[48:51], v[40:43], v[0:15]
	v_cvt_pk_bf16_f32 v23, v39, v52
	s_nop 11
	v_add_f32_e32 v0, v156, v0
	v_mul_f32_e32 v0, v0, v24
	v_and_b32_e32 v24, 0xffff0000, v108
	v_add_f32_e32 v1, v156, v1
	v_mul_f32_e32 v1, v1, v24
	v_lshlrev_b32_e32 v24, 16, v109
	v_add_f32_e32 v2, v156, v2
	v_mul_f32_e32 v2, v2, v24
	v_and_b32_e32 v24, 0xffff0000, v109
	v_add_f32_e32 v3, v156, v3
	v_mul_f32_e32 v24, v3, v24
	v_mul_f32_e32 v3, v1, v1
	v_mul_f32_e32 v26, v24, v24
	v_fmac_f32_e32 v3, v0, v0
	v_fmac_f32_e32 v26, v2, v2
	v_add_f32_e32 v3, v3, v26
	v_add_f32_e32 v25, v25, v3
	v_cvt_pk_bf16_f32 v3, v0, v1
	v_lshlrev_b32_e32 v0, 16, v104
	v_add_f32_e32 v1, v156, v4
	v_mul_f32_e32 v0, v1, v0
	v_and_b32_e32 v1, 0xffff0000, v104
	v_add_f32_e32 v4, v156, v5
	v_mul_f32_e32 v1, v4, v1
	v_lshlrev_b32_e32 v4, 16, v105
	v_add_f32_e32 v5, v156, v6
	v_mul_f32_e32 v4, v5, v4
	v_and_b32_e32 v5, 0xffff0000, v105
	v_add_f32_e32 v6, v156, v7
	v_mul_f32_e32 v6, v6, v5
	v_mul_f32_e32 v5, v1, v1
	v_mul_f32_e32 v7, v6, v6
	v_fmac_f32_e32 v5, v0, v0
	v_fmac_f32_e32 v7, v4, v4
	v_add_f32_e32 v5, v5, v7
	v_add_f32_e32 v7, v5, v25
	v_cvt_pk_bf16_f32 v5, v0, v1
	v_lshlrev_b32_e32 v0, 16, v78
	v_add_f32_e32 v1, v156, v8
	v_cvt_pk_bf16_f32 v4, v4, v6
	v_mul_f32_e32 v0, v1, v0
	v_and_b32_e32 v1, 0xffff0000, v78
	v_add_f32_e32 v6, v156, v9
	v_mul_f32_e32 v1, v6, v1
	v_lshlrev_b32_e32 v6, 16, v79
	v_add_f32_e32 v8, v156, v10
	v_mul_f32_e32 v8, v8, v6
	v_and_b32_e32 v6, 0xffff0000, v79
	v_add_f32_e32 v9, v156, v11
	v_mul_f32_e32 v9, v9, v6
	v_mul_f32_e32 v6, v1, v1
	v_mul_f32_e32 v10, v9, v9
	v_fmac_f32_e32 v6, v0, v0
	v_fmac_f32_e32 v10, v8, v8
	v_add_f32_e32 v6, v6, v10
	v_add_f32_e32 v7, v6, v7
	v_cvt_pk_bf16_f32 v6, v0, v1
	v_lshlrev_b32_e32 v0, 16, v76
	v_add_f32_e32 v1, v156, v12
	v_mul_f32_e32 v0, v1, v0
	v_and_b32_e32 v1, 0xffff0000, v76
	v_add_f32_e32 v10, v156, v13
	v_mul_f32_e32 v11, v10, v1
	v_lshlrev_b32_e32 v1, 16, v77
	v_add_f32_e32 v10, v156, v14
	v_mul_f32_e32 v12, v10, v1
	v_and_b32_e32 v1, 0xffff0000, v77
	v_add_f32_e32 v10, v156, v15
	v_mul_f32_e32 v13, v10, v1
	v_mul_f32_e32 v1, v11, v11
	v_mul_f32_e32 v10, v13, v13
	v_fmac_f32_e32 v1, v0, v0
	v_fmac_f32_e32 v10, v12, v12
	v_add_f32_e32 v1, v1, v10
	v_add_f32_e32 v1, v1, v7
	ds_bpermute_b32 v10, v188, v1
	v_cvt_pk_bf16_f32 v9, v8, v9
	v_cvt_pk_bf16_f32 v8, v0, v11
	v_lshlrev_b32_e32 v0, 3, v132
	v_cvt_pk_bf16_f32 v2, v2, v24
	v_cvt_pk_bf16_f32 v7, v12, v13
	s_and_saveexec_b64 s[28:29], s[8:9]
	s_cbranch_execz .LBB0_601
	s_lshl_b32 s0, s13, 2
	s_add_i32 s0, s0, 0
	s_waitcnt lgkmcnt(0)
	v_add_f32_e32 v1, v1, v10
	v_add_u32_e32 v10, s0, v0
	ds_write_b32 v10, v1 offset:34880
.LBB0_601:
	s_or_b64 exec, exec, s[28:29]
	v_add_u32_e32 v52, 0, v0
	s_mov_b64 s[0:1], s[80:81]
	s_waitcnt lgkmcnt(0)
	s_barrier
	ds_read_b64 v[50:51], v52 offset:34880
	s_load_dwordx2 s[0:1], s[0:1], 0xc0
	v_or_b32_e32 v10, s26, v88
	v_ashrrev_i32_e32 v11, 31, v10
	s_waitcnt lgkmcnt(0)
	s_barrier
	v_lshl_add_u64 v[0:1], v[10:11], 2, s[0:1]
	global_load_dwordx4 v[12:15], v[0:1], off
	global_load_dwordx4 v[24:27], v[0:1], off offset:32
	global_load_dwordx4 v[28:31], v[0:1], off offset:64
	global_load_dwordx4 v[38:41], v[0:1], off offset:96
	global_load_dwordx4 v[42:45], v[0:1], off offset:128
	global_load_dwordx4 v[46:49], v[0:1], off offset:160
	v_mul_u32_u24_e32 v11, 0x408, v132
	v_lshlrev_b32_e32 v10, 1, v10
	v_add3_u32 v10, v52, v11, v10
	v_add_f32_e32 v11, v50, v51
	v_fmamk_f32 v11, v11, 0x3b000000, v177
	v_mul_f32_e32 v50, 0x4b800000, v11
	v_cmp_gt_f32_e32 vcc, s38, v11
	v_lshlrev_b32_e32 v62, 16, v97
	v_and_b32_e32 v63, 0xffff0000, v97
	v_cndmask_b32_e32 v11, v11, v50, vcc
	global_load_dwordx4 v[50:53], v[0:1], off offset:192
	global_load_dwordx4 v[54:57], v[0:1], off offset:224
	global_load_dwordx4 v[58:61], v[0:1], off offset:512
	v_rsq_f32_e32 v11, v11
	v_lshlrev_b32_e32 v64, 16, v82
	v_and_b32_e32 v65, 0xffff0000, v82
	v_lshlrev_b32_e32 v66, 16, v134
	v_mul_f32_e32 v78, 0x45800000, v11
	v_cndmask_b32_e32 v11, v11, v78, vcc
	v_and_b32_e32 v67, 0xffff0000, v134
	v_lshlrev_b32_e32 v68, 16, v133
	v_and_b32_e32 v69, 0xffff0000, v133
	v_mul_f32_e32 v62, v11, v62
	v_mul_f32_e32 v63, v11, v63
	v_mul_f32_e32 v64, v11, v64
	v_mul_f32_e32 v65, v11, v65
	v_lshlrev_b32_e32 v70, 16, v136
	v_and_b32_e32 v71, 0xffff0000, v136
	v_lshlrev_b32_e32 v72, 16, v135
	v_and_b32_e32 v73, 0xffff0000, v135
	v_lshlrev_b32_e32 v74, 16, v138
	v_and_b32_e32 v75, 0xffff0000, v138
	v_lshlrev_b32_e32 v76, 16, v137
	v_and_b32_e32 v77, 0xffff0000, v137
	v_mul_f32_e32 v66, v11, v66
	v_mul_f32_e32 v67, v11, v67
	v_mul_f32_e32 v68, v11, v68
	v_mul_f32_e32 v69, v11, v69
	v_mul_f32_e32 v70, v11, v70
	v_mul_f32_e32 v71, v11, v71
	v_mul_f32_e32 v72, v11, v72
	v_mul_f32_e32 v73, v11, v73
	v_mul_f32_e32 v74, v11, v74
	v_mul_f32_e32 v75, v11, v75
	v_mul_f32_e32 v76, v11, v76
	v_mul_f32_e32 v77, v11, v77
	s_mov_b64 s[0:1], s[80:81]
	s_lshl_b32 s28, s42, 4
	s_ashr_i32 s13, s12, 31
	s_ashr_i32 s29, s28, 31
	s_lshl_b64 s[26:27], s[12:13], 11
	s_mulk_i32 s42, 0x4100
	s_waitcnt vmcnt(8)
	v_mul_f32_e32 v12, v12, v62
	v_mul_f32_e32 v13, v13, v63
	v_mul_f32_e32 v14, v14, v64
	v_mul_f32_e32 v15, v15, v65
	s_waitcnt vmcnt(7)
	v_mul_f32_e32 v24, v66, v24
	v_mul_f32_e32 v25, v67, v25
	v_mul_f32_e32 v26, v68, v26
	v_mul_f32_e32 v27, v69, v27
	v_cvt_pk_bf16_f32 v12, v12, v13
	v_cvt_pk_bf16_f32 v13, v14, v15
	v_cvt_pk_bf16_f32 v14, v24, v25
	v_cvt_pk_bf16_f32 v15, v26, v27
	s_waitcnt vmcnt(6)
	v_mul_f32_e32 v28, v70, v28
	v_mul_f32_e32 v29, v71, v29
	v_mul_f32_e32 v30, v72, v30
	v_mul_f32_e32 v31, v73, v31
	s_waitcnt vmcnt(5)
; __device__ __forceinline__ float bf_lo(unsigned w) { return __uint_as_float(w << 16); }
; __device__ __forceinline__ float bf_hi(unsigned w) { return __uint_as_float(w & 0xffff0000u); }
; #define LAS __attribute__((address_space(3)))
; __device__ __forceinline__ unsigned cvt_pk_nv(float lo, float hi) { unsigned r; asm("v_cvt_pk_bf16_f32 %0, %1, %2" : "=v"(r) : "v"(lo), "v"(hi)); return r; }
; __device__ __forceinline__ void gmlp_tile(const Ctx& C, int T, LAS unsigned char* lds, int wave, int lane, int tid) {
;     ...
; #pragma unroll
;     for (int h = 0; h < 4; ++h)
; #pragma unroll
;         for (int dbi = 0; dbi < 2; ++dbi)
; #pragma unroll
;             for (int rg = 0; rg < 4; ++rg) {
;                 const int c = h * 128 + 32 * (2 * dh + dbi) + 8 * rg + 4 * hh;
;                 const v4f ga = *(const v4f*)(gap + c);
;                 const unsigned w0 = outp[h][dbi][2 * rg], w1 = outp[h][dbi][2 * rg + 1];
;                 v2u o; o.x = cvt_pk_nv(bf_lo(w0) * rstd * ga.x, bf_hi(w0) * rstd * ga.y); o.y = cvt_pk_nv(bf_lo(w1) * rstd * ga.z, bf_hi(w1) * rstd * ga.w);
;                 *(LAS v2u*)(OT + t * OT_STRIDE + c) = o;
;             }
	v_mul_f32_e32 v38, v74, v38
	v_mul_f32_e32 v39, v75, v39
	v_mul_f32_e32 v40, v76, v40
	v_mul_f32_e32 v41, v77, v41
	v_cvt_pk_bf16_f32 v24, v28, v29
	v_cvt_pk_bf16_f32 v25, v30, v31
	v_cvt_pk_bf16_f32 v26, v38, v39
	v_cvt_pk_bf16_f32 v27, v40, v41
	ds_write2_b64 v10, v[12:13], v[14:15] offset1:2
	ds_write2_b64 v10, v[24:25], v[26:27] offset0:4 offset1:6
	global_load_dwordx4 v[12:15], v[0:1], off offset:544
	v_lshlrev_b32_e32 v24, 16, v103
	v_and_b32_e32 v25, 0xffff0000, v103
	v_mul_f32_e32 v24, v11, v24
	v_mul_f32_e32 v25, v11, v25
	s_waitcnt vmcnt(5)
	v_mul_f32_e32 v24, v24, v42
	v_mul_f32_e32 v25, v25, v43
	v_cvt_pk_bf16_f32 v28, v24, v25
	v_lshlrev_b32_e32 v24, 16, v101
	v_and_b32_e32 v25, 0xffff0000, v101
	v_lshlrev_b32_e32 v30, 16, v145
	v_and_b32_e32 v31, 0xffff0000, v145
	v_mul_f32_e32 v24, v11, v24
	v_mul_f32_e32 v25, v11, v25
	v_mul_f32_e32 v30, v11, v30
	v_mul_f32_e32 v31, v11, v31
	v_mul_f32_e32 v24, v24, v44
	v_mul_f32_e32 v25, v25, v45
	s_waitcnt vmcnt(4)
	v_mul_f32_e32 v30, v30, v46
	v_mul_f32_e32 v31, v31, v47
	v_cvt_pk_bf16_f32 v29, v24, v25
	global_load_dwordx4 v[24:27], v[0:1], off offset:576
	v_cvt_pk_bf16_f32 v30, v30, v31
	v_lshlrev_b32_e32 v31, 16, v142
	v_mul_f32_e32 v31, v11, v31
	v_and_b32_e32 v38, 0xffff0000, v142
	v_mul_f32_e32 v31, v31, v48
	v_mul_f32_e32 v38, v11, v38
	v_mul_f32_e32 v38, v38, v49
	v_cvt_pk_bf16_f32 v31, v31, v38
	ds_write2_b64 v10, v[28:29], v[30:31] offset0:8 offset1:10
	global_load_dwordx4 v[28:31], v[0:1], off offset:608
	v_lshlrev_b32_e32 v38, 16, v146
	v_and_b32_e32 v39, 0xffff0000, v146
	v_mul_f32_e32 v38, v11, v38
	v_mul_f32_e32 v39, v11, v39
	s_waitcnt vmcnt(5)
	v_mul_f32_e32 v38, v38, v50
	v_mul_f32_e32 v39, v39, v51
	v_cvt_pk_bf16_f32 v42, v38, v39
	v_lshlrev_b32_e32 v38, 16, v143
	v_and_b32_e32 v39, 0xffff0000, v143
	v_mul_f32_e32 v38, v11, v38
	v_mul_f32_e32 v39, v11, v39
	v_mul_f32_e32 v38, v38, v52
	v_mul_f32_e32 v39, v39, v53
	v_cvt_pk_bf16_f32 v43, v38, v39
	global_load_dwordx4 v[38:41], v[0:1], off offset:640
	v_lshlrev_b32_e32 v44, 16, v147
	v_and_b32_e32 v45, 0xffff0000, v147
	v_mul_f32_e32 v44, v11, v44
	v_mul_f32_e32 v45, v11, v45
	s_waitcnt vmcnt(5)
	v_mul_f32_e32 v44, v44, v54
	v_mul_f32_e32 v45, v45, v55
	v_cvt_pk_bf16_f32 v44, v44, v45
	v_lshlrev_b32_e32 v45, 16, v144
	v_mul_f32_e32 v45, v11, v45
	v_and_b32_e32 v46, 0xffff0000, v144
	v_mul_f32_e32 v45, v45, v56
	v_mul_f32_e32 v46, v11, v46
	v_mul_f32_e32 v46, v46, v57
	v_cvt_pk_bf16_f32 v45, v45, v46
	ds_write2_b64 v10, v[42:43], v[44:45] offset0:12 offset1:14
	global_load_dwordx4 v[42:45], v[0:1], off offset:672
	v_lshlrev_b32_e32 v46, 16, v141
	v_and_b32_e32 v47, 0xffff0000, v141
	v_mul_f32_e32 v46, v11, v46
	v_mul_f32_e32 v47, v11, v47
	v_lshlrev_b32_e32 v52, 16, v153
	s_waitcnt vmcnt(5)
	v_mul_f32_e32 v46, v46, v58
	v_mul_f32_e32 v47, v47, v59
	v_mul_f32_e32 v52, v11, v52
	v_cvt_pk_bf16_f32 v50, v46, v47
	v_lshlrev_b32_e32 v46, 16, v140
	v_and_b32_e32 v47, 0xffff0000, v140
	v_mul_f32_e32 v46, v11, v46
	v_mul_f32_e32 v47, v11, v47
	v_mul_f32_e32 v46, v46, v60
	v_mul_f32_e32 v47, v47, v61
	v_cvt_pk_bf16_f32 v51, v46, v47
	global_load_dwordx4 v[46:49], v[0:1], off offset:704
	s_waitcnt vmcnt(5)
	v_mul_f32_e32 v12, v52, v12
	v_and_b32_e32 v52, 0xffff0000, v153
	v_mul_f32_e32 v52, v11, v52
	v_mul_f32_e32 v13, v52, v13
	v_cvt_pk_bf16_f32 v12, v12, v13
	v_lshlrev_b32_e32 v13, 16, v150
	v_mul_f32_e32 v13, v11, v13
	v_mul_f32_e32 v13, v13, v14
	v_and_b32_e32 v14, 0xffff0000, v150
	v_mul_f32_e32 v14, v11, v14
	v_mul_f32_e32 v14, v14, v15
	v_cvt_pk_bf16_f32 v13, v13, v14
	ds_write2_b64 v10, v[50:51], v[12:13] offset0:32 offset1:34
	global_load_dwordx4 v[12:15], v[0:1], off offset:736
	v_lshlrev_b32_e32 v50, 16, v154
	v_mul_f32_e32 v50, v11, v50
	v_lshlrev_b32_e32 v52, 16, v155
	v_mul_f32_e32 v52, v11, v52
	s_waitcnt vmcnt(5)
	v_mul_f32_e32 v24, v50, v24
	v_and_b32_e32 v50, 0xffff0000, v154
	v_mul_f32_e32 v50, v11, v50
	v_mul_f32_e32 v25, v50, v25
	v_cvt_pk_bf16_f32 v50, v24, v25
	v_lshlrev_b32_e32 v24, 16, v151
	v_and_b32_e32 v25, 0xffff0000, v151
	v_mul_f32_e32 v24, v11, v24
	v_mul_f32_e32 v25, v11, v25
	v_mul_f32_e32 v24, v24, v26
	s_waitcnt vmcnt(4)
	v_mul_f32_e32 v28, v52, v28
	v_and_b32_e32 v52, 0xffff0000, v155
	v_mul_f32_e32 v25, v25, v27
	v_mul_f32_e32 v52, v11, v52
	v_cvt_pk_bf16_f32 v51, v24, v25
	global_load_dwordx4 v[24:27], v[0:1], off offset:1024
	v_mul_f32_e32 v29, v52, v29
	v_cvt_pk_bf16_f32 v28, v28, v29
	v_lshlrev_b32_e32 v29, 16, v152
	v_mul_f32_e32 v29, v11, v29
	v_mul_f32_e32 v29, v29, v30
	v_and_b32_e32 v30, 0xffff0000, v152
	v_mul_f32_e32 v30, v11, v30
	v_mul_f32_e32 v30, v30, v31
	v_cvt_pk_bf16_f32 v29, v29, v30
	ds_write2_b64 v10, v[50:51], v[28:29] offset0:36 offset1:38
	global_load_dwordx4 v[28:31], v[0:1], off offset:1056
	v_lshlrev_b32_e32 v50, 16, v149
	v_mul_f32_e32 v50, v11, v50
	s_waitcnt vmcnt(5)
	v_mul_f32_e32 v38, v50, v38
	v_and_b32_e32 v50, 0xffff0000, v149
	v_mul_f32_e32 v50, v11, v50
	v_mul_f32_e32 v39, v50, v39
	v_cvt_pk_bf16_f32 v50, v38, v39
	v_lshlrev_b32_e32 v38, 16, v148
	v_and_b32_e32 v39, 0xffff0000, v148
	v_mul_f32_e32 v38, v11, v38
	v_mul_f32_e32 v39, v11, v39
	v_mul_f32_e32 v38, v38, v40
	v_mul_f32_e32 v39, v39, v41
	v_cvt_pk_bf16_f32 v51, v38, v39
	global_load_dwordx4 v[38:41], v[0:1], off offset:1088
	v_lshlrev_b32_e32 v52, 16, v160
	v_mul_f32_e32 v52, v11, v52
	s_waitcnt vmcnt(5)
	v_mul_f32_e32 v42, v52, v42
	v_and_b32_e32 v52, 0xffff0000, v160
	v_mul_f32_e32 v52, v11, v52
	v_mul_f32_e32 v43, v52, v43
	v_cvt_pk_bf16_f32 v42, v42, v43
	v_lshlrev_b32_e32 v43, 16, v157
	v_mul_f32_e32 v43, v11, v43
	v_mul_f32_e32 v43, v43, v44
	v_and_b32_e32 v44, 0xffff0000, v157
	v_mul_f32_e32 v44, v11, v44
	v_mul_f32_e32 v44, v44, v45
	v_cvt_pk_bf16_f32 v43, v43, v44
	ds_write2_b64 v10, v[50:51], v[42:43] offset0:40 offset1:42
	global_load_dwordx4 v[42:45], v[0:1], off offset:1120
	v_lshlrev_b32_e32 v50, 16, v161
	v_mul_f32_e32 v50, v11, v50
	s_waitcnt vmcnt(5)
; __device__ __forceinline__ float bf_lo(unsigned w) { return __uint_as_float(w << 16); }
; __device__ __forceinline__ float bf_hi(unsigned w) { return __uint_as_float(w & 0xffff0000u); }
; #define LAS __attribute__((address_space(3)))
; __device__ __forceinline__ unsigned cvt_pk_nv(float lo, float hi) { unsigned r; asm("v_cvt_pk_bf16_f32 %0, %1, %2" : "=v"(r) : "v"(lo), "v"(hi)); return r; }
; __device__ __forceinline__ void gmlp_tile(const Ctx& C, int T, LAS unsigned char* lds, int wave, int lane, int tid) {
;     ...
; #pragma unroll
;     for (int h = 0; h < 4; ++h)
; #pragma unroll
;         for (int dbi = 0; dbi < 2; ++dbi)
; #pragma unroll
;             for (int rg = 0; rg < 4; ++rg) {
;                 const int c = h * 128 + 32 * (2 * dh + dbi) + 8 * rg + 4 * hh;
;                 const v4f ga = *(const v4f*)(gap + c);
;                 const unsigned w0 = outp[h][dbi][2 * rg], w1 = outp[h][dbi][2 * rg + 1];
;                 v2u o; o.x = cvt_pk_nv(bf_lo(w0) * rstd * ga.x, bf_hi(w0) * rstd * ga.y); o.y = cvt_pk_nv(bf_lo(w1) * rstd * ga.z, bf_hi(w1) * rstd * ga.w);
;                 *(LAS v2u*)(OT + t * OT_STRIDE + c) = o;
;             }
	v_mul_f32_e32 v46, v50, v46
	v_and_b32_e32 v50, 0xffff0000, v161
	v_mul_f32_e32 v50, v11, v50
	v_mul_f32_e32 v47, v50, v47
	v_cvt_pk_bf16_f32 v50, v46, v47
	v_lshlrev_b32_e32 v46, 16, v158
	v_and_b32_e32 v47, 0xffff0000, v158
	v_lshlrev_b32_e32 v52, 16, v162
	v_mul_f32_e32 v46, v11, v46
	v_mul_f32_e32 v47, v11, v47
	v_mul_f32_e32 v52, v11, v52
	v_mul_f32_e32 v46, v46, v48
	v_mul_f32_e32 v47, v47, v49
	s_waitcnt vmcnt(4)
	v_mul_f32_e32 v12, v52, v12
	v_and_b32_e32 v52, 0xffff0000, v162
	v_cvt_pk_bf16_f32 v51, v46, v47
	global_load_dwordx4 v[46:49], v[0:1], off offset:1152
	v_mul_f32_e32 v52, v11, v52
	v_mul_f32_e32 v13, v52, v13
	v_cvt_pk_bf16_f32 v12, v12, v13
	v_lshlrev_b32_e32 v13, 16, v159
	v_mul_f32_e32 v13, v11, v13
	v_mul_f32_e32 v13, v13, v14
	v_and_b32_e32 v14, 0xffff0000, v159
	v_mul_f32_e32 v14, v11, v14
	v_mul_f32_e32 v14, v14, v15
	v_cvt_pk_bf16_f32 v13, v13, v14
	ds_write2_b64 v10, v[50:51], v[12:13] offset0:44 offset1:46
	v_lshlrev_b32_e32 v50, 16, v131
	v_mul_f32_e32 v50, v11, v50
	global_load_dwordx4 v[12:15], v[0:1], off offset:1184
	v_lshlrev_b32_e32 v52, 16, v129
	v_mul_f32_e32 v52, v11, v52
	s_waitcnt vmcnt(5)
	v_mul_f32_e32 v24, v50, v24
	v_and_b32_e32 v50, 0xffff0000, v131
	v_mul_f32_e32 v50, v11, v50
	v_mul_f32_e32 v25, v50, v25
	v_cvt_pk_bf16_f32 v50, v24, v25
	v_lshlrev_b32_e32 v24, 16, v130
	v_and_b32_e32 v25, 0xffff0000, v130
	v_mul_f32_e32 v24, v11, v24
	v_mul_f32_e32 v25, v11, v25
	v_mul_f32_e32 v24, v24, v26
	v_mul_f32_e32 v25, v25, v27
	v_cvt_pk_bf16_f32 v51, v24, v25
	global_load_dwordx4 v[24:27], v[0:1], off offset:1216
	s_waitcnt vmcnt(5)
	v_mul_f32_e32 v28, v52, v28
	v_and_b32_e32 v52, 0xffff0000, v129
	v_mul_f32_e32 v52, v11, v52
	v_mul_f32_e32 v29, v52, v29
	v_cvt_pk_bf16_f32 v28, v28, v29
	v_lshlrev_b32_e32 v29, 16, v128
	v_mul_f32_e32 v29, v11, v29
	v_mul_f32_e32 v29, v29, v30
	v_and_b32_e32 v30, 0xffff0000, v128
	v_mul_f32_e32 v30, v11, v30
	v_mul_f32_e32 v30, v30, v31
	v_cvt_pk_bf16_f32 v29, v29, v30
	ds_write2_b64 v10, v[50:51], v[28:29] offset0:64 offset1:66
	global_load_dwordx4 v[28:31], v[0:1], off offset:1248
	v_lshlrev_b32_e32 v50, 16, v127
	v_mul_f32_e32 v50, v11, v50
	s_waitcnt vmcnt(5)
	v_mul_f32_e32 v38, v50, v38
	v_and_b32_e32 v50, 0xffff0000, v127
	v_mul_f32_e32 v50, v11, v50
	v_mul_f32_e32 v39, v50, v39
	v_cvt_pk_bf16_f32 v50, v38, v39
	v_lshlrev_b32_e32 v38, 16, v126
	v_and_b32_e32 v39, 0xffff0000, v126
	v_mul_f32_e32 v38, v11, v38
	v_mul_f32_e32 v39, v11, v39
	v_mul_f32_e32 v38, v38, v40
	v_mul_f32_e32 v39, v39, v41
	v_cvt_pk_bf16_f32 v51, v38, v39
	global_load_dwordx4 v[38:41], v[0:1], off offset:1536
	v_lshlrev_b32_e32 v52, 16, v125
	v_mul_f32_e32 v52, v11, v52
	s_waitcnt vmcnt(5)
	v_mul_f32_e32 v42, v52, v42
	v_and_b32_e32 v52, 0xffff0000, v125
	v_mul_f32_e32 v52, v11, v52
	v_mul_f32_e32 v43, v52, v43
	v_cvt_pk_bf16_f32 v42, v42, v43
	v_lshlrev_b32_e32 v43, 16, v124
	v_mul_f32_e32 v43, v11, v43
	v_mul_f32_e32 v43, v43, v44
	v_and_b32_e32 v44, 0xffff0000, v124
	v_mul_f32_e32 v44, v11, v44
	v_mul_f32_e32 v44, v44, v45
	v_cvt_pk_bf16_f32 v43, v43, v44
	ds_write2_b64 v10, v[50:51], v[42:43] offset0:68 offset1:70
	v_lshlrev_b32_e32 v50, 16, v107
	v_mul_f32_e32 v50, v11, v50
	global_load_dwordx4 v[42:45], v[0:1], off offset:1568
	v_lshlrev_b32_e32 v52, 16, v35
	s_waitcnt vmcnt(5)
	v_mul_f32_e32 v46, v50, v46
	v_and_b32_e32 v50, 0xffff0000, v107
	v_mul_f32_e32 v50, v11, v50
	v_mul_f32_e32 v47, v50, v47
	v_cvt_pk_bf16_f32 v50, v46, v47
	v_lshlrev_b32_e32 v46, 16, v106
	v_and_b32_e32 v47, 0xffff0000, v106
	v_mul_f32_e32 v46, v11, v46
	v_mul_f32_e32 v47, v11, v47
	v_mul_f32_e32 v46, v46, v48
	v_mul_f32_e32 v47, v47, v49
	v_cvt_pk_bf16_f32 v51, v46, v47
	global_load_dwordx4 v[46:49], v[0:1], off offset:1600
	v_and_b32_e32 v35, 0xffff0000, v35
	v_mul_f32_e32 v52, v11, v52
	v_mul_f32_e32 v35, v11, v35
	s_waitcnt vmcnt(5)
	v_mul_f32_e32 v12, v52, v12
	v_mul_f32_e32 v13, v35, v13
	v_cvt_pk_bf16_f32 v52, v12, v13
	v_lshlrev_b32_e32 v12, 16, v32
	v_and_b32_e32 v13, 0xffff0000, v32
	v_mul_f32_e32 v12, v11, v12
	v_mul_f32_e32 v13, v11, v13
	v_mul_f32_e32 v12, v12, v14
	v_mul_f32_e32 v13, v13, v15
	v_cvt_pk_bf16_f32 v53, v12, v13
	global_load_dwordx4 v[12:15], v[0:1], off offset:1632
	v_lshlrev_b32_e32 v32, 16, v36
	v_mul_f32_e32 v32, v11, v32
	ds_write2_b64 v10, v[50:51], v[52:53] offset0:72 offset1:74
	s_waitcnt vmcnt(5)
	v_mul_f32_e32 v24, v32, v24
	v_and_b32_e32 v32, 0xffff0000, v36
	v_mul_f32_e32 v32, v11, v32
	v_mul_f32_e32 v25, v32, v25
	v_cvt_pk_bf16_f32 v50, v24, v25
	v_lshlrev_b32_e32 v24, 16, v33
	v_mul_f32_e32 v24, v11, v24
	v_mul_f32_e32 v32, v24, v26
	v_and_b32_e32 v24, 0xffff0000, v33
	v_mul_f32_e32 v24, v11, v24
	v_mul_f32_e32 v33, v24, v27
	v_cvt_pk_bf16_f32 v51, v32, v33
	v_lshlrev_b32_e32 v32, 16, v37
	global_load_dwordx4 v[24:27], v[0:1], off offset:1664
	v_mul_f32_e32 v32, v11, v32
	s_waitcnt vmcnt(5)
; __device__ __forceinline__ float bf_lo(unsigned w) { return __uint_as_float(w << 16); }
; __device__ __forceinline__ float bf_hi(unsigned w) { return __uint_as_float(w & 0xffff0000u); }
; #define LAS __attribute__((address_space(3)))
; __device__ __forceinline__ unsigned cvt_pk_nv(float lo, float hi) { unsigned r; asm("v_cvt_pk_bf16_f32 %0, %1, %2" : "=v"(r) : "v"(lo), "v"(hi)); return r; }
; __device__ __forceinline__ void gmlp_tile(const Ctx& C, int T, LAS unsigned char* lds, int wave, int lane, int tid) {
;     ...
; #pragma unroll
;     for (int h = 0; h < 4; ++h)
; #pragma unroll
;         for (int dbi = 0; dbi < 2; ++dbi)
; #pragma unroll
;             for (int rg = 0; rg < 4; ++rg) {
;                 const int c = h * 128 + 32 * (2 * dh + dbi) + 8 * rg + 4 * hh;
;                 const v4f ga = *(const v4f*)(gap + c);
;                 const unsigned w0 = outp[h][dbi][2 * rg], w1 = outp[h][dbi][2 * rg + 1];
;                 v2u o; o.x = cvt_pk_nv(bf_lo(w0) * rstd * ga.x, bf_hi(w0) * rstd * ga.y); o.y = cvt_pk_nv(bf_lo(w1) * rstd * ga.z, bf_hi(w1) * rstd * ga.w);
;                 *(LAS v2u*)(OT + t * OT_STRIDE + c) = o;
;             }
;     __syncthreads();
;     {
;         bf16* obase = C.MIX() + (size_t)r0 * DM;
; #pragma unroll 4
;         for (int i = 0; i < 16; ++i) { const int row = wave * 16 + i; *(v4u*)(obase + (size_t)row * DM + 8 * lane) = *(const LAS v4u*)(OT + row * OT_STRIDE + 8 * lane); }
	v_mul_f32_e32 v28, v32, v28
	v_and_b32_e32 v32, 0xffff0000, v37
	v_mul_f32_e32 v32, v11, v32
	v_mul_f32_e32 v29, v32, v29
	v_cvt_pk_bf16_f32 v28, v28, v29
	v_lshlrev_b32_e32 v29, 16, v34
	v_mul_f32_e32 v29, v11, v29
	v_mul_f32_e32 v29, v29, v30
	v_and_b32_e32 v30, 0xffff0000, v34
	global_load_dwordx4 v[32:35], v[0:1], off offset:1696
	v_mul_f32_e32 v30, v11, v30
	v_mul_f32_e32 v30, v30, v31
	v_cvt_pk_bf16_f32 v29, v29, v30
	ds_write2_b64 v10, v[50:51], v[28:29] offset0:76 offset1:78
	v_lshlrev_b32_e32 v28, 16, v17
	v_mul_f32_e32 v28, v11, v28
	v_and_b32_e32 v17, 0xffff0000, v17
	s_waitcnt vmcnt(5)
	v_mul_f32_e32 v28, v28, v38
	v_mul_f32_e32 v17, v11, v17
	v_mul_f32_e32 v17, v17, v39
	v_cvt_pk_bf16_f32 v50, v28, v17
	global_load_dwordx4 v[28:31], v[0:1], off offset:1728
	global_load_dwordx4 v[36:39], v[0:1], off offset:1760
	v_lshlrev_b32_e32 v17, 16, v16
	v_and_b32_e32 v16, 0xffff0000, v16
	v_mul_f32_e32 v17, v11, v17
	v_mul_f32_e32 v16, v11, v16
	v_mul_f32_e32 v17, v17, v40
	v_mul_f32_e32 v16, v16, v41
	v_cvt_pk_bf16_f32 v51, v17, v16
	v_lshlrev_b32_e32 v16, 16, v20
	v_and_b32_e32 v17, 0xffff0000, v20
	v_mul_f32_e32 v16, v11, v16
	v_mul_f32_e32 v17, v11, v17
	s_waitcnt vmcnt(6)
	v_mul_f32_e32 v16, v16, v42
	v_mul_f32_e32 v17, v17, v43
	v_cvt_pk_bf16_f32 v16, v16, v17
	v_lshlrev_b32_e32 v17, 16, v18
	v_and_b32_e32 v0, 0xffff0000, v18
	v_mul_f32_e32 v17, v11, v17
	v_mul_f32_e32 v0, v11, v0
	v_mul_f32_e32 v17, v17, v44
	v_mul_f32_e32 v0, v0, v45
	v_cvt_pk_bf16_f32 v17, v17, v0
	v_lshlrev_b32_e32 v0, 16, v21
	v_and_b32_e32 v1, 0xffff0000, v21
	v_mul_f32_e32 v0, v11, v0
	v_mul_f32_e32 v1, v11, v1
	s_waitcnt vmcnt(5)
	v_mul_f32_e32 v0, v0, v46
	v_mul_f32_e32 v1, v1, v47
	ds_write2_b64 v10, v[50:51], v[16:17] offset0:96 offset1:98
	v_cvt_pk_bf16_f32 v0, v0, v1
	v_lshlrev_b32_e32 v1, 16, v19
	v_and_b32_e32 v16, 0xffff0000, v19
	v_mul_f32_e32 v1, v11, v1
	v_mul_f32_e32 v16, v11, v16
	v_mul_f32_e32 v1, v1, v48
	v_mul_f32_e32 v16, v16, v49
	v_cvt_pk_bf16_f32 v1, v1, v16
	v_lshlrev_b32_e32 v16, 16, v23
	v_mul_f32_e32 v16, v11, v16
	s_waitcnt vmcnt(4)
	v_mul_f32_e32 v12, v16, v12
	v_and_b32_e32 v16, 0xffff0000, v23
	v_mul_f32_e32 v16, v11, v16
	v_mul_f32_e32 v13, v16, v13
	v_cvt_pk_bf16_f32 v12, v12, v13
	v_lshlrev_b32_e32 v13, 16, v22
	v_mul_f32_e32 v13, v11, v13
	v_mul_f32_e32 v13, v13, v14
	v_and_b32_e32 v14, 0xffff0000, v22
	v_mul_f32_e32 v14, v11, v14
	v_mul_f32_e32 v14, v14, v15
	v_cvt_pk_bf16_f32 v13, v13, v14
	ds_write2_b64 v10, v[0:1], v[12:13] offset0:100 offset1:102
	v_lshlrev_b32_e32 v0, 16, v3
	v_and_b32_e32 v1, 0xffff0000, v3
	v_mul_f32_e32 v0, v11, v0
	v_mul_f32_e32 v1, v11, v1
	s_waitcnt vmcnt(3)
	v_mul_f32_e32 v0, v0, v24
	v_mul_f32_e32 v1, v1, v25
	v_cvt_pk_bf16_f32 v0, v0, v1
	v_lshlrev_b32_e32 v1, 16, v2
	v_and_b32_e32 v2, 0xffff0000, v2
	v_mul_f32_e32 v1, v11, v1
	v_mul_f32_e32 v2, v11, v2
	v_mul_f32_e32 v1, v1, v26
	v_mul_f32_e32 v2, v2, v27
	v_cvt_pk_bf16_f32 v1, v1, v2
	v_lshlrev_b32_e32 v2, 16, v5
	v_and_b32_e32 v3, 0xffff0000, v5
	v_mul_f32_e32 v2, v11, v2
	v_mul_f32_e32 v3, v11, v3
	s_waitcnt vmcnt(2)
	v_mul_f32_e32 v2, v2, v32
	v_mul_f32_e32 v3, v3, v33
	v_cvt_pk_bf16_f32 v2, v2, v3
	v_lshlrev_b32_e32 v3, 16, v4
	v_mul_f32_e32 v3, v11, v3
	v_and_b32_e32 v4, 0xffff0000, v4
	v_mul_f32_e32 v3, v3, v34
	v_mul_f32_e32 v4, v11, v4
	v_mul_f32_e32 v4, v4, v35
	v_cvt_pk_bf16_f32 v3, v3, v4
	ds_write2_b64 v10, v[0:1], v[2:3] offset0:104 offset1:106
	v_lshlrev_b32_e32 v0, 16, v6
	v_and_b32_e32 v1, 0xffff0000, v6
	v_mul_f32_e32 v0, v11, v0
	v_mul_f32_e32 v1, v11, v1
	s_waitcnt vmcnt(1)
	v_mul_f32_e32 v0, v0, v28
	v_mul_f32_e32 v1, v1, v29
	v_cvt_pk_bf16_f32 v0, v0, v1
	v_lshlrev_b32_e32 v1, 16, v9
	v_and_b32_e32 v2, 0xffff0000, v9
	v_mul_f32_e32 v1, v11, v1
	v_mul_f32_e32 v2, v11, v2
	v_mul_f32_e32 v1, v1, v30
	v_mul_f32_e32 v2, v2, v31
	v_cvt_pk_bf16_f32 v1, v1, v2
	v_lshlrev_b32_e32 v2, 16, v8
	v_and_b32_e32 v3, 0xffff0000, v8
	v_mul_f32_e32 v2, v11, v2
	v_mul_f32_e32 v3, v11, v3
	s_waitcnt vmcnt(0)
	v_mul_f32_e32 v2, v2, v36
	v_mul_f32_e32 v3, v3, v37
	v_cvt_pk_bf16_f32 v2, v2, v3
	v_lshlrev_b32_e32 v3, 16, v7
	v_mul_f32_e32 v3, v11, v3
	v_and_b32_e32 v4, 0xffff0000, v7
	v_mul_f32_e32 v3, v3, v38
	v_mul_f32_e32 v4, v11, v4
	v_mul_f32_e32 v4, v4, v39
	v_cvt_pk_bf16_f32 v3, v3, v4
	ds_write2_b64 v10, v[0:1], v[2:3] offset0:108 offset1:110
	s_waitcnt lgkmcnt(0)
	s_barrier
	s_load_dwordx2 s[0:1], s[0:1], 0x110
	v_add_u32_e32 v2, s42, v176
	s_waitcnt lgkmcnt(0)
	v_lshl_add_u64 v[0:1], s[0:1], 0, v[92:93]
	s_lshl_b64 s[0:1], s[28:29], 11
	s_add_u32 s0, s26, s0
	s_addc_u32 s1, s27, s1
	v_lshl_add_u64 v[0:1], v[0:1], 0, s[0:1]
	s_mov_b64 s[26:27], 0
